# memory-attention loop: softmax exp / row-sum / pack moved from a block between QK and PV into the 16 PV MFMA gaps (only P fragment 0 prepared ahead)
# baseline (speedup 1.0000x reference)
; template <int KS> __device__ __forceinline__ void pv_ks(f32x16* o, int vb, bf16x8 pa) {
;     const s16x4 l0 = tr_read<v_rd_off(0, KS, 0)>(vb), h0 = tr_read<v_rd_off(0, KS, 1)>(vb), l1 = tr_read<v_rd_off(1, KS, 0)>(vb), h1 = tr_read<v_rd_off(1, KS, 1)>(vb);
;     const s16x4 l2 = tr_read<v_rd_off(2, KS, 0)>(vb), h2 = tr_read<v_rd_off(2, KS, 1)>(vb), l3 = tr_read<v_rd_off(3, KS, 0)>(vb), h3 = tr_read<v_rd_off(3, KS, 1)>(vb);
;     ...
;     asm volatile("s_waitcnt lgkmcnt(6)" ::: "memory"); SBAR();
;     o[0] = __builtin_amdgcn_mfma_f32_32x32x16_bf16(pa, PK(l0, h0), o[0], 0, 0, 0);
;     asm volatile("s_waitcnt lgkmcnt(4)" ::: "memory"); SBAR();
;     o[1] = __builtin_amdgcn_mfma_f32_32x32x16_bf16(pa, PK(l1, h1), o[1], 0, 0, 0);
;     asm volatile("s_waitcnt lgkmcnt(2)" ::: "memory"); SBAR();
;     o[2] = __builtin_amdgcn_mfma_f32_32x32x16_bf16(pa, PK(l2, h2), o[2], 0, 0, 0);
;     asm volatile("s_waitcnt lgkmcnt(0)" ::: "memory"); SBAR();
;     o[3] = __builtin_amdgcn_mfma_f32_32x32x16_bf16(pa, PK(l3, h3), o[3], 0, 0, 0);
;     ...
; }
; __device__ __forceinline__ void pv_d0(f32x16* o, int vb, bf16x8 pa0, bf16x8 pa1, bf16x8 pa2, bf16x8 pa3) {
;     __builtin_amdgcn_s_setprio(1);
;     pv_ks<0>(o, vb, pa0); pv_ks<1>(o, vb, pa1); pv_ks<2>(o, vb, pa2); pv_ks<3>(o, vb, pa3);
;     __builtin_amdgcn_s_setprio(0);
; }
; __device__ __forceinline__ void exp_half(f32x16& p) {
; #pragma unroll
;     for (int r = 0; r < 16; ++r) p[r] = __builtin_amdgcn_exp2f(p[r]);
; }
; __device__ __forceinline__ void pack_p(const f32x16& p0, const f32x16& p1, float& l_reg, bf16x8& pa0, bf16x8& pa1, bf16x8& pa2, bf16x8& pa3) {
;     float ps = 0;
; #pragma unroll
;     for (int r = 0; r < 16; ++r) ps += p0[r];
; #pragma unroll
;     for (int r = 0; r < 16; ++r) ps += p1[r];
;     l_reg += ps;
;     ...
;     PK4(p0, 0, pa0); PK4(p0, 8, pa1); PK4(p1, 0, pa2); PK4(p1, 8, pa3);
;     ...
; }
; template <int ND0> __device__ __forceinline__ void qkt(f32x16& p0, f32x16& p1, const char* Ks, const bf16x8* qr, int r32, int hi, int colB0) {
; #pragma unroll
;     for (int d0 = 0; d0 < ND0; ++d0) { const int cb = colB0 + (d0 * 16 + hi * 8) * 2;
;         const bf16x8 b0 = *reinterpret_cast<const bf16x8*>(Ks + KSWZ(r32, cb));
;         const bf16x8 b1 = *reinterpret_cast<const bf16x8*>(Ks + KSWZ(32 + r32, cb));
;         p0 = __builtin_amdgcn_mfma_f32_32x32x16_bf16(b0, qr[d0], p0, 0, 0, 0);
.LBB0_200:
	s_add_i32 s100, s2, 0x10000
	v_add_u32_e32 v210, s100, v156
	ds_read_b128 v[178:181], v210
	ds_read_b128 v[182:185], v210 offset:8192
	v_add_u32_e32 v210, s100, v155
	ds_read_b128 v[186:189], v210
	ds_read_b128 v[190:193], v210 offset:8192
	v_add_u32_e32 v210, s100, v154
	ds_read_b128 v[194:197], v210
	ds_read_b128 v[198:201], v210 offset:8192
	v_add_u32_e32 v210, s100, v153
	ds_read_b128 v[202:205], v210
	ds_read_b128 v[206:209], v210 offset:8192
	s_waitcnt lgkmcnt(7)
	v_mfma_f32_32x32x16_bf16 v[96:111], v[178:181], v[112:115], v[64:79]
	v_add_u32_e32 v210, s100, v152
	ds_read_b128 v[178:181], v210
	s_waitcnt lgkmcnt(7)
	v_mfma_f32_32x32x16_bf16 v[80:95], v[182:185], v[112:115], v[64:79]
	ds_read_b128 v[182:185], v210 offset:8192
	s_waitcnt lgkmcnt(7)
	v_mfma_f32_32x32x16_bf16 v[96:111], v[186:189], v[116:119], v[96:111]
	v_add_u32_e32 v210, s100, v151
	ds_read_b128 v[186:189], v210
	s_waitcnt lgkmcnt(7)
	v_mfma_f32_32x32x16_bf16 v[80:95], v[190:193], v[116:119], v[80:95]
	ds_read_b128 v[190:193], v210 offset:8192
	s_waitcnt lgkmcnt(7)
	v_mfma_f32_32x32x16_bf16 v[96:111], v[194:197], v[120:123], v[96:111]
	v_add_u32_e32 v210, s100, v150
	ds_read_b128 v[194:197], v210
	s_waitcnt lgkmcnt(7)
	v_mfma_f32_32x32x16_bf16 v[80:95], v[198:201], v[120:123], v[80:95]
	ds_read_b128 v[198:201], v210 offset:8192
	s_waitcnt lgkmcnt(7)
	v_mfma_f32_32x32x16_bf16 v[96:111], v[202:205], v[124:127], v[96:111]
	v_add_u32_e32 v210, s100, v149
	ds_read_b128 v[202:205], v210
	s_waitcnt lgkmcnt(7)
	v_mfma_f32_32x32x16_bf16 v[80:95], v[206:209], v[124:127], v[80:95]
	ds_read_b128 v[206:209], v210 offset:8192
	s_waitcnt lgkmcnt(7)
	v_mfma_f32_32x32x16_bf16 v[96:111], v[178:181], v[128:131], v[96:111]
	s_waitcnt lgkmcnt(6)
	v_mfma_f32_32x32x16_bf16 v[80:95], v[182:185], v[128:131], v[80:95]
	s_waitcnt lgkmcnt(5)
	v_mfma_f32_32x32x16_bf16 v[96:111], v[186:189], v[132:135], v[96:111]
	s_waitcnt lgkmcnt(4)
	v_mfma_f32_32x32x16_bf16 v[80:95], v[190:193], v[132:135], v[80:95]
	s_waitcnt lgkmcnt(3)
	v_mfma_f32_32x32x16_bf16 v[96:111], v[194:197], v[136:139], v[96:111]
	s_waitcnt lgkmcnt(2)
	v_mfma_f32_32x32x16_bf16 v[80:95], v[198:201], v[136:139], v[80:95]
	s_waitcnt lgkmcnt(1)
	v_mfma_f32_32x32x16_bf16 v[96:111], v[202:205], v[140:143], v[96:111]
	s_waitcnt lgkmcnt(0)
	v_mfma_f32_32x32x16_bf16 v[80:95], v[206:209], v[140:143], v[80:95]
	v_add_u32_e32 v211, s2, v147
	ds_read_b64_tr_b16 v[178:179], v211 offset:0
	ds_read_b64_tr_b16 v[180:181], v211 offset:2048
	ds_read_b64_tr_b16 v[182:183], v211 offset:512
	ds_read_b64_tr_b16 v[184:185], v211 offset:2560
	ds_read_b64_tr_b16 v[186:187], v211 offset:1024
	ds_read_b64_tr_b16 v[188:189], v211 offset:3072
	ds_read_b64_tr_b16 v[190:191], v211 offset:1536
	ds_read_b64_tr_b16 v[192:193], v211 offset:3584
	s_nop 9
	v_exp_f32_e32 v96, v96
	v_exp_f32_e32 v97, v97
	v_exp_f32_e32 v98, v98
	v_exp_f32_e32 v99, v99
	v_exp_f32_e32 v100, v100
	v_exp_f32_e32 v101, v101
	v_exp_f32_e32 v102, v102
	v_exp_f32_e32 v103, v103
	v_exp_f32_e32 v157, v80
	v_exp_f32_e32 v158, v81
	v_exp_f32_e32 v159, v82
	v_exp_f32_e32 v160, v83
	v_exp_f32_e32 v161, v84
	v_exp_f32_e32 v162, v85
	v_exp_f32_e32 v163, v86
	v_exp_f32_e32 v164, v87
	v_cvt_pk_bf16_f32 v80, v96, v97
	v_cvt_pk_bf16_f32 v81, v98, v99
	v_cvt_pk_bf16_f32 v82, v100, v101
	v_cvt_pk_bf16_f32 v83, v102, v103
	v_add_f32_e32 v212, v96, v97
	v_add_f32_e32 v212, v98, v212
	s_setprio 1
	s_waitcnt lgkmcnt(6)
	v_mfma_f32_32x32x16_bf16 v[48:63], v[80:83], v[178:181], v[48:63]
	ds_read_b64_tr_b16 v[194:195], v211 offset:4096
	ds_read_b64_tr_b16 v[196:197], v211 offset:6144
	v_add_f32_e32 v212, v99, v212
	v_add_f32_e32 v212, v100, v212
	v_add_f32_e32 v212, v101, v212
	v_add_f32_e32 v212, v102, v212
	v_add_f32_e32 v212, v103, v212
	s_waitcnt lgkmcnt(6)
	v_mfma_f32_32x32x16_bf16 v[32:47], v[80:83], v[182:185], v[32:47]
	ds_read_b64_tr_b16 v[198:199], v211 offset:4608
	ds_read_b64_tr_b16 v[200:201], v211 offset:6656
	v_exp_f32_e32 v104, v104
	v_exp_f32_e32 v105, v105
	v_exp_f32_e32 v106, v106
	v_exp_f32_e32 v107, v107
	v_exp_f32_e32 v108, v108
	s_waitcnt lgkmcnt(6)
	v_mfma_f32_32x32x16_bf16 v[16:31], v[80:83], v[186:189], v[16:31]
	ds_read_b64_tr_b16 v[202:203], v211 offset:5120
	ds_read_b64_tr_b16 v[204:205], v211 offset:7168
	v_exp_f32_e32 v109, v109
	v_exp_f32_e32 v110, v110
	v_exp_f32_e32 v111, v111
	v_add_f32_e32 v212, v104, v212
	v_add_f32_e32 v212, v105, v212
	s_waitcnt lgkmcnt(6)
	v_mfma_f32_32x32x16_bf16 v[0:15], v[80:83], v[190:193], v[0:15]
	ds_read_b64_tr_b16 v[206:207], v211 offset:5632
	ds_read_b64_tr_b16 v[208:209], v211 offset:7680
	v_cvt_pk_bf16_f32 v84, v104, v105
	v_cvt_pk_bf16_f32 v85, v106, v107
	v_cvt_pk_bf16_f32 v86, v108, v109
	v_cvt_pk_bf16_f32 v87, v110, v111
	v_add_f32_e32 v212, v106, v212
	s_waitcnt lgkmcnt(6)
	v_mfma_f32_32x32x16_bf16 v[48:63], v[84:87], v[194:197], v[48:63]
	ds_read_b64_tr_b16 v[178:179], v211 offset:8192
	ds_read_b64_tr_b16 v[180:181], v211 offset:10240
	v_add_f32_e32 v212, v107, v212
	v_add_f32_e32 v212, v108, v212
	v_add_f32_e32 v212, v109, v212
	v_add_f32_e32 v212, v110, v212
	v_add_f32_e32 v212, v111, v212
	s_waitcnt lgkmcnt(6)
	v_mfma_f32_32x32x16_bf16 v[32:47], v[84:87], v[198:201], v[32:47]
	ds_read_b64_tr_b16 v[182:183], v211 offset:8704
	ds_read_b64_tr_b16 v[184:185], v211 offset:10752
	v_exp_f32_e32 v165, v88
	v_exp_f32_e32 v166, v89
	v_exp_f32_e32 v167, v90
	v_exp_f32_e32 v168, v91
	v_exp_f32_e32 v169, v92
	s_waitcnt lgkmcnt(6)
	v_mfma_f32_32x32x16_bf16 v[16:31], v[84:87], v[202:205], v[16:31]
	ds_read_b64_tr_b16 v[186:187], v211 offset:9216
	ds_read_b64_tr_b16 v[188:189], v211 offset:11264
	v_exp_f32_e32 v170, v93
	v_exp_f32_e32 v171, v94
	v_exp_f32_e32 v95, v95
	v_add_f32_e32 v212, v157, v212
	v_add_f32_e32 v212, v95, v212
	s_waitcnt lgkmcnt(6)
; #define SBAR() __builtin_amdgcn_sched_barrier(0)
; template <int KS> __device__ __forceinline__ void pv_ks(f32x16* o, int vb, bf16x8 pa) {
;     const s16x4 l0 = tr_read<v_rd_off(0, KS, 0)>(vb), h0 = tr_read<v_rd_off(0, KS, 1)>(vb), l1 = tr_read<v_rd_off(1, KS, 0)>(vb), h1 = tr_read<v_rd_off(1, KS, 1)>(vb);
;     const s16x4 l2 = tr_read<v_rd_off(2, KS, 0)>(vb), h2 = tr_read<v_rd_off(2, KS, 1)>(vb), l3 = tr_read<v_rd_off(3, KS, 0)>(vb), h3 = tr_read<v_rd_off(3, KS, 1)>(vb);
;     ...
;     asm volatile("s_waitcnt lgkmcnt(6)" ::: "memory"); SBAR();
;     o[0] = __builtin_amdgcn_mfma_f32_32x32x16_bf16(pa, PK(l0, h0), o[0], 0, 0, 0);
;     asm volatile("s_waitcnt lgkmcnt(4)" ::: "memory"); SBAR();
;     o[1] = __builtin_amdgcn_mfma_f32_32x32x16_bf16(pa, PK(l1, h1), o[1], 0, 0, 0);
;     asm volatile("s_waitcnt lgkmcnt(2)" ::: "memory"); SBAR();
;     o[2] = __builtin_amdgcn_mfma_f32_32x32x16_bf16(pa, PK(l2, h2), o[2], 0, 0, 0);
;     asm volatile("s_waitcnt lgkmcnt(0)" ::: "memory"); SBAR();
;     o[3] = __builtin_amdgcn_mfma_f32_32x32x16_bf16(pa, PK(l3, h3), o[3], 0, 0, 0);
;     ...
; }
; __device__ __forceinline__ void pv_d0(f32x16* o, int vb, bf16x8 pa0, bf16x8 pa1, bf16x8 pa2, bf16x8 pa3) {
;     __builtin_amdgcn_s_setprio(1);
;     pv_ks<0>(o, vb, pa0); pv_ks<1>(o, vb, pa1); pv_ks<2>(o, vb, pa2); pv_ks<3>(o, vb, pa3);
;     __builtin_amdgcn_s_setprio(0);
; }
; __device__ __forceinline__ void exp_half(f32x16& p) {
; #pragma unroll
;     for (int r = 0; r < 16; ++r) p[r] = __builtin_amdgcn_exp2f(p[r]);
; }
; __device__ __forceinline__ void mem_unit(const MemArgs& A, int unit, char* lds, int wv) {
;     ...
;     { auto rr = __builtin_amdgcn_permlane32_swap(__float_as_uint(l_reg), __float_as_uint(l_reg), false, false);
;       l_reg = __uint_as_float(rr[0]) + __uint_as_float(rr[1]); }
;     if (hi == 0) wsl[r32] = l_reg;
;     asm volatile("s_waitcnt lgkmcnt(0)" ::: "memory");
; #pragma unroll
;     for (int r = 0; r < 16; ++r) { const int rr_ = crow(r, hi); const float rl = 1.0f / wsl[rr_];
;         const bf16* gp = A.proj + (grow0 + rr_) * INC + C_MG + hm * 128 + r32; bf16* yp = A.y + (grow0 + rr_) * DM + Y_M + hm * 128 + r32;
; #pragma unroll
;         for (int d0 = 0; d0 < 4; ++d0) { const float g = bf2f(gp[d0 * 32]); const float val = o[d0][r] * rl * silu(g);
;             yp[d0 * 32] = (bf16)(cvtpk(val, val) & 0xffffu); } }
	v_mfma_f32_32x32x16_bf16 v[0:15], v[84:87], v[206:209], v[0:15]
	ds_read_b64_tr_b16 v[190:191], v211 offset:9728
	ds_read_b64_tr_b16 v[192:193], v211 offset:11776
	v_cvt_pk_bf16_f32 v88, v157, v158
	v_cvt_pk_bf16_f32 v89, v159, v160
	v_cvt_pk_bf16_f32 v90, v161, v162
	v_cvt_pk_bf16_f32 v91, v163, v164
	v_cvt_pk_bf16_f32 v92, v165, v166
	s_waitcnt lgkmcnt(6)
	v_mfma_f32_32x32x16_bf16 v[48:63], v[88:91], v[178:181], v[48:63]
	ds_read_b64_tr_b16 v[194:195], v211 offset:12288
	ds_read_b64_tr_b16 v[196:197], v211 offset:14336
	v_cvt_pk_bf16_f32 v93, v167, v168
	v_cvt_pk_bf16_f32 v94, v169, v170
	v_cvt_pk_bf16_f32 v95, v171, v95
	s_waitcnt lgkmcnt(6)
	v_mfma_f32_32x32x16_bf16 v[32:47], v[88:91], v[182:185], v[32:47]
	ds_read_b64_tr_b16 v[198:199], v211 offset:12800
	ds_read_b64_tr_b16 v[200:201], v211 offset:14848
	v_add_f32_e32 v212, v158, v212
	v_add_f32_e32 v212, v159, v212
	v_add_f32_e32 v212, v160, v212
	s_waitcnt lgkmcnt(6)
	v_mfma_f32_32x32x16_bf16 v[16:31], v[88:91], v[186:189], v[16:31]
	ds_read_b64_tr_b16 v[202:203], v211 offset:13312
	ds_read_b64_tr_b16 v[204:205], v211 offset:15360
	v_add_f32_e32 v212, v161, v212
	v_add_f32_e32 v212, v162, v212
	s_waitcnt lgkmcnt(6)
	v_mfma_f32_32x32x16_bf16 v[0:15], v[88:91], v[190:193], v[0:15]
	ds_read_b64_tr_b16 v[206:207], v211 offset:13824
	ds_read_b64_tr_b16 v[208:209], v211 offset:15872
	v_add_f32_e32 v212, v163, v212
	v_add_f32_e32 v212, v164, v212
	s_waitcnt lgkmcnt(6)
	v_mfma_f32_32x32x16_bf16 v[48:63], v[92:95], v[194:197], v[48:63]
	v_add_f32_e32 v212, v165, v212
	v_add_f32_e32 v212, v166, v212
	s_waitcnt lgkmcnt(4)
	v_mfma_f32_32x32x16_bf16 v[32:47], v[92:95], v[198:201], v[32:47]
	v_add_f32_e32 v212, v167, v212
	v_add_f32_e32 v212, v168, v212
	s_waitcnt lgkmcnt(2)
	v_mfma_f32_32x32x16_bf16 v[16:31], v[92:95], v[202:205], v[16:31]
	v_add_f32_e32 v212, v169, v212
	v_add_f32_e32 v212, v170, v212
	s_waitcnt lgkmcnt(0)
	v_mfma_f32_32x32x16_bf16 v[0:15], v[92:95], v[206:209], v[0:15]
	v_add_f32_e32 v212, v171, v212
	v_add_f32_e32 v148, v148, v212
	s_setprio 0
	s_addk_i32 s2, 0x4000
	s_cmp_lg_u32 s2, 0x10000
	s_cbranch_scc1 .LBB0_200
	s_and_b32 s1, s1, 0x3fffffc0
	s_lshl_b32 s1, s1, 2
	s_add_i32 s1, s1, 0
	v_mov_b32_e32 v64, v148
	s_add_i32 s1, s1, 0x20000
	s_nop 0
	v_permlane32_swap_b32_e32 v148, v64
	v_cmp_gt_u32_e32 vcc, 32, v145
	s_and_saveexec_b64 s[6:7], vcc
	v_add_f32_e32 v64, v148, v64
	v_lshl_add_u32 v65, v144, 2, s1
	ds_write_b32 v65, v64
	s_or_b64 exec, exec, s[6:7]
	s_waitcnt lgkmcnt(0)
	v_lshl_add_u32 v72, v146, 4, s1
	ds_read_b128 v[64:67], v72
	s_lshl_b32 s84, s0, 1
	v_lshlrev_b32_e32 v176, 1, v144
	s_waitcnt lgkmcnt(0)
	v_div_scale_f32 v68, s[6:7], v64, v64, 1.0
	v_rcp_f32_e32 v69, v68
	s_nop 0
	v_fma_f32 v70, -v68, v69, 1.0
	v_fmac_f32_e32 v69, v70, v69
	v_div_scale_f32 v70, vcc, 1.0, v64, 1.0
	v_mul_f32_e32 v71, v70, v69
	v_fma_f32 v73, -v68, v71, v70
	v_fmac_f32_e32 v71, v73, v69
	v_fma_f32 v68, -v68, v71, v70
	v_div_fmas_f32 v68, v68, v69, v71
	v_div_fixup_f32 v64, v68, v64, 1.0
	v_lshl_or_b32 v68, v146, 2, s8
	v_mul_u32_u24_e32 v161, 0x3800, v68
	v_add_u32_e32 v161, s84, v161
	v_lshl_add_u32 v161, v144, 1, v161
	v_add_u32_e32 v161, 0x3400, v161
	global_load_ushort v84, v161, s[80:81]
	global_load_ushort v85, v161, s[80:81] offset:64
	global_load_ushort v86, v161, s[80:81] offset:128
	global_load_ushort v87, v161, s[80:81] offset:192
	v_add_u32_e32 v163, 0x3800, v161
	global_load_ushort v88, v163, s[80:81]
	global_load_ushort v89, v163, s[80:81] offset:64
	global_load_ushort v90, v163, s[80:81] offset:128
	global_load_ushort v91, v163, s[80:81] offset:192
	v_add_u32_e32 v162, 0x7000, v161
	global_load_ushort v92, v162, s[80:81]
	global_load_ushort v93, v162, s[80:81] offset:64
	global_load_ushort v94, v162, s[80:81] offset:128
	global_load_ushort v95, v162, s[80:81] offset:192
	v_add_u32_e32 v163, 0xa800, v161
	global_load_ushort v96, v163, s[80:81]
	global_load_ushort v97, v163, s[80:81] offset:64
	global_load_ushort v98, v163, s[80:81] offset:128
	global_load_ushort v99, v163, s[80:81] offset:192
	v_add_u32_e32 v162, 0x1c000, v161
	global_load_ushort v100, v162, s[80:81]
	global_load_ushort v101, v162, s[80:81] offset:64
	global_load_ushort v102, v162, s[80:81] offset:128
	global_load_ushort v103, v162, s[80:81] offset:192
	v_add_u32_e32 v163, 0x1f800, v161
	global_load_ushort v104, v163, s[80:81]
	global_load_ushort v105, v163, s[80:81] offset:64
	global_load_ushort v106, v163, s[80:81] offset:128
	global_load_ushort v107, v163, s[80:81] offset:192
	v_add_u32_e32 v162, 0x23000, v161
	global_load_ushort v108, v162, s[80:81]
	global_load_ushort v109, v162, s[80:81] offset:64
	global_load_ushort v110, v162, s[80:81] offset:128
	global_load_ushort v111, v162, s[80:81] offset:192
	v_add_u32_e32 v163, 0x26800, v161
	global_load_ushort v157, v163, s[80:81]
	global_load_ushort v158, v163, s[80:81] offset:64
	global_load_ushort v159, v163, s[80:81] offset:128
	global_load_ushort v160, v163, s[80:81] offset:192
	v_mov_b64_e32 v[70:71], s[80:81]
	v_mad_u64_u32 v[74:75], s[6:7], v68, s33, v[70:71]
	s_mul_i32 s6, s3, 0x3800
	s_nop 0
	v_add_u32_e32 v75, s6, v75
	v_lshl_add_u64 v[74:75], v[74:75], 0, s[84:85]
	v_mov_b32_e32 v69, s3
	v_lshl_add_u64 v[74:75], v[74:75], 0, v[176:177]
	s_mov_b64 s[2:3], 0x3400
	v_lshl_add_u64 v[76:77], v[74:75], 0, s[2:3]
	v_add_co_u32_e32 v74, vcc, s63, v74
	v_lshlrev_b64 v[78:79], 12, v[68:69]
	s_nop 0
	v_addc_co_u32_e32 v75, vcc, 0, v75, vcc
	s_waitcnt vmcnt(28)
; __device__ __forceinline__ int crow(int r, int hi) { return (r & 3) + 8 * (r >> 2) + 4 * hi; }
; __device__ __forceinline__ unsigned cvtpk(float lo, float hi) { f32x2_t v = {lo, hi}; bf16x2_t b = __builtin_convertvector(v, bf16x2_t); return __builtin_bit_cast(unsigned, b); }
; __device__ __forceinline__ float bf2f(unsigned short h) { return __uint_as_float(((unsigned)h) << 16); }
; __device__ __forceinline__ float silu(float x) { return x / (1.0f + __expf(-x)); }
; __device__ __forceinline__ void mem_unit(const MemArgs& A, int unit, char* lds, int wv) {
;     ...
;     if (hi == 0) wsl[r32] = l_reg;
;     asm volatile("s_waitcnt lgkmcnt(0)" ::: "memory");
; #pragma unroll
;     for (int r = 0; r < 16; ++r) { const int rr_ = crow(r, hi); const float rl = 1.0f / wsl[rr_];
;         const bf16* gp = A.proj + (grow0 + rr_) * INC + C_MG + hm * 128 + r32; bf16* yp = A.y + (grow0 + rr_) * DM + Y_M + hm * 128 + r32;
; #pragma unroll
;         for (int d0 = 0; d0 < 4; ++d0) { const float g = bf2f(gp[d0 * 32]); const float val = o[d0][r] * rl * silu(g);
;             yp[d0 * 32] = (bf16)(cvtpk(val, val) & 0xffffu); } }
;     __syncthreads();
	v_mov_b32_e32 v73, v84
	v_lshl_add_u64 v[78:79], s[82:83], 0, v[78:79]
	v_mul_f32_e32 v48, v48, v64
	v_lshl_add_u64 v[78:79], v[78:79], 0, s[84:85]
	v_lshl_add_u64 v[78:79], v[78:79], 0, v[176:177]
	v_mul_f32_e32 v32, v32, v64
	v_mul_f32_e32 v16, v16, v64
	v_mul_f32_e32 v0, v0, v64
	s_nop 0
	v_lshlrev_b32_e32 v73, 16, v73
	v_mul_f32_e32 v74, 0xbfb8aa3b, v73
	v_exp_f32_e32 v74, v74
	s_nop 0
	v_add_f32_e32 v74, 1.0, v74
	v_div_scale_f32 v75, s[0:1], v74, v74, v73
	v_rcp_f32_e32 v80, v75
	s_nop 0
	v_fma_f32 v81, -v75, v80, 1.0
	v_fmac_f32_e32 v80, v81, v80
	v_div_scale_f32 v81, vcc, v73, v74, v73
	v_mul_f32_e32 v82, v81, v80
	v_fma_f32 v83, -v75, v82, v81
	v_fmac_f32_e32 v82, v83, v80
	v_fma_f32 v75, -v75, v82, v81
	v_div_fmas_f32 v75, v75, v80, v82
	v_div_fixup_f32 v73, v75, v74, v73
	v_mul_f32_e32 v48, v48, v73
	v_cvt_pk_bf16_f32 v48, v48, s0
	global_store_short v[78:79], v48, off offset:3072
	s_waitcnt vmcnt(28)
	v_mov_b32_e32 v48, v85
	s_nop 0
	v_lshlrev_b32_e32 v48, 16, v48
	v_mul_f32_e32 v73, 0xbfb8aa3b, v48
	v_exp_f32_e32 v73, v73
	s_nop 0
	v_add_f32_e32 v73, 1.0, v73
	v_div_scale_f32 v74, s[0:1], v73, v73, v48
	v_rcp_f32_e32 v75, v74
	s_nop 0
	v_fma_f32 v80, -v74, v75, 1.0
	v_fmac_f32_e32 v75, v80, v75
	v_div_scale_f32 v80, vcc, v48, v73, v48
	v_mul_f32_e32 v81, v80, v75
	v_fma_f32 v82, -v74, v81, v80
	v_fmac_f32_e32 v81, v82, v75
	v_fma_f32 v74, -v74, v81, v80
	v_div_fmas_f32 v74, v74, v75, v81
	v_div_fixup_f32 v48, v74, v73, v48
	v_mul_f32_e32 v32, v32, v48
	v_cvt_pk_bf16_f32 v32, v32, s0
	global_store_short v[78:79], v32, off offset:3136
	s_waitcnt vmcnt(28)
	v_mov_b32_e32 v32, v86
	s_nop 0
	v_lshlrev_b32_e32 v32, 16, v32
	v_mul_f32_e32 v48, 0xbfb8aa3b, v32
	v_exp_f32_e32 v48, v48
	s_nop 0
	v_add_f32_e32 v48, 1.0, v48
	v_div_scale_f32 v73, s[0:1], v48, v48, v32
	v_rcp_f32_e32 v74, v73
	s_nop 0
	v_fma_f32 v75, -v73, v74, 1.0
	v_fmac_f32_e32 v74, v75, v74
	v_div_scale_f32 v75, vcc, v32, v48, v32
	v_mul_f32_e32 v80, v75, v74
	v_fma_f32 v81, -v73, v80, v75
	v_fmac_f32_e32 v80, v81, v74
	v_fma_f32 v73, -v73, v80, v75
	v_div_fmas_f32 v73, v73, v74, v80
	v_div_fixup_f32 v32, v73, v48, v32
	v_mul_f32_e32 v16, v16, v32
	v_cvt_pk_bf16_f32 v16, v16, s0
	global_store_short v[78:79], v16, off offset:3200
	s_waitcnt vmcnt(28)
	v_mov_b32_e32 v16, v87
	s_nop 0
	v_lshlrev_b32_e32 v16, 16, v16
	v_mul_f32_e32 v32, 0xbfb8aa3b, v16
	v_exp_f32_e32 v32, v32
	s_nop 0
	v_add_f32_e32 v32, 1.0, v32
	v_div_scale_f32 v48, s[0:1], v32, v32, v16
	v_rcp_f32_e32 v64, v48
	s_nop 0
	v_fma_f32 v73, -v48, v64, 1.0
	v_fmac_f32_e32 v64, v73, v64
	v_div_scale_f32 v73, vcc, v16, v32, v16
	v_mul_f32_e32 v74, v73, v64
	v_fma_f32 v75, -v48, v74, v73
	v_fmac_f32_e32 v74, v75, v64
	v_fma_f32 v48, -v48, v74, v73
	v_div_fmas_f32 v48, v48, v64, v74
	v_div_fixup_f32 v16, v48, v32, v16
	v_mul_f32_e32 v0, v0, v16
	v_cvt_pk_bf16_f32 v0, v0, s0
	global_store_short v[78:79], v0, off offset:3264
	v_div_scale_f32 v0, s[0:1], v65, v65, 1.0
	v_rcp_f32_e32 v16, v0
	s_nop 0
	v_fma_f32 v32, -v0, v16, 1.0
	v_fmac_f32_e32 v16, v32, v16
	v_div_scale_f32 v32, vcc, 1.0, v65, 1.0
	v_mul_f32_e32 v48, v32, v16
	v_fma_f32 v64, -v0, v48, v32
	v_fmac_f32_e32 v48, v64, v16
	v_or_b32_e32 v64, 1, v68
	v_mad_u64_u32 v[74:75], s[0:1], v64, s33, v[70:71]
	v_add_u32_e32 v75, s6, v75
	v_lshl_add_u64 v[74:75], v[74:75], 0, s[84:85]
	v_fma_f32 v0, -v0, v48, v32
	v_lshl_add_u64 v[74:75], v[74:75], 0, v[176:177]
	v_div_fmas_f32 v0, v0, v16, v48
	v_lshl_add_u64 v[76:77], v[74:75], 0, s[2:3]
	v_add_co_u32_e32 v74, vcc, s63, v74
	v_div_fixup_f32 v0, v0, v65, 1.0
	s_nop 0
	v_addc_co_u32_e32 v75, vcc, 0, v75, vcc
	s_waitcnt vmcnt(28)
	v_mov_b32_e32 v16, v88
	v_mul_f32_e32 v32, v49, v0
	v_mov_b32_e32 v65, v69
	v_lshlrev_b64 v[64:65], 12, v[64:65]
	v_lshl_add_u64 v[64:65], s[82:83], 0, v[64:65]
	v_lshl_add_u64 v[64:65], v[64:65], 0, s[84:85]
	v_lshl_add_u64 v[64:65], v[64:65], 0, v[176:177]
	v_mul_f32_e32 v17, v17, v0
	s_nop 0
	v_lshlrev_b32_e32 v16, 16, v16
	v_mul_f32_e32 v48, 0xbfb8aa3b, v16
	v_exp_f32_e32 v48, v48
	s_nop 0
	v_add_f32_e32 v48, 1.0, v48
	v_div_scale_f32 v49, s[0:1], v48, v48, v16
	v_rcp_f32_e32 v73, v49
	s_nop 0
	v_fma_f32 v74, -v49, v73, 1.0
	v_fmac_f32_e32 v73, v74, v73
	v_div_scale_f32 v74, vcc, v16, v48, v16
	v_mul_f32_e32 v75, v74, v73
	v_fma_f32 v78, -v49, v75, v74
	v_fmac_f32_e32 v75, v78, v73
	v_fma_f32 v49, -v49, v75, v74
	v_div_fmas_f32 v49, v49, v73, v75
	v_div_fixup_f32 v16, v49, v48, v16
	v_mul_f32_e32 v16, v32, v16
	v_cvt_pk_bf16_f32 v16, v16, s0
	global_store_short v[64:65], v16, off offset:3072
	s_waitcnt vmcnt(28)
	v_mov_b32_e32 v16, v89
	v_mul_f32_e32 v32, v33, v0
	v_mul_f32_e32 v0, v1, v0
	s_nop 0
	v_lshlrev_b32_e32 v16, 16, v16
	v_mul_f32_e32 v33, 0xbfb8aa3b, v16
	v_exp_f32_e32 v33, v33
	s_nop 0
	v_add_f32_e32 v33, 1.0, v33
	v_div_scale_f32 v48, s[0:1], v33, v33, v16
	v_rcp_f32_e32 v49, v48
	s_nop 0
	v_fma_f32 v73, -v48, v49, 1.0
	v_fmac_f32_e32 v49, v73, v49
	v_div_scale_f32 v73, vcc, v16, v33, v16
	v_mul_f32_e32 v74, v73, v49
	v_fma_f32 v75, -v48, v74, v73
	v_fmac_f32_e32 v74, v75, v49
	v_fma_f32 v48, -v48, v74, v73
	v_div_fmas_f32 v48, v48, v49, v74
	v_div_fixup_f32 v16, v48, v33, v16
	v_mul_f32_e32 v16, v32, v16
	v_cvt_pk_bf16_f32 v16, v16, s0
	global_store_short v[64:65], v16, off offset:3136
	s_waitcnt vmcnt(28)
	v_mov_b32_e32 v16, v90
	s_nop 0
	v_lshlrev_b32_e32 v16, 16, v16
	v_mul_f32_e32 v32, 0xbfb8aa3b, v16
	v_exp_f32_e32 v32, v32
	s_nop 0
	v_add_f32_e32 v32, 1.0, v32
	v_div_scale_f32 v33, s[0:1], v32, v32, v16
	v_rcp_f32_e32 v48, v33
	s_nop 0
	v_fma_f32 v49, -v33, v48, 1.0
	v_fmac_f32_e32 v48, v49, v48
	v_div_scale_f32 v49, vcc, v16, v32, v16
	v_mul_f32_e32 v73, v49, v48
	v_fma_f32 v74, -v33, v73, v49
	v_fmac_f32_e32 v73, v74, v48
	v_fma_f32 v33, -v33, v73, v49
	v_div_fmas_f32 v33, v33, v48, v73
	v_div_fixup_f32 v16, v33, v32, v16
	v_mul_f32_e32 v16, v17, v16
	v_cvt_pk_bf16_f32 v16, v16, s0
	global_store_short v[64:65], v16, off offset:3200
	s_waitcnt vmcnt(28)
; __device__ __forceinline__ int crow(int r, int hi) { return (r & 3) + 8 * (r >> 2) + 4 * hi; }
; __device__ __forceinline__ unsigned cvtpk(float lo, float hi) { f32x2_t v = {lo, hi}; bf16x2_t b = __builtin_convertvector(v, bf16x2_t); return __builtin_bit_cast(unsigned, b); }
; __device__ __forceinline__ float bf2f(unsigned short h) { return __uint_as_float(((unsigned)h) << 16); }
; __device__ __forceinline__ float silu(float x) { return x / (1.0f + __expf(-x)); }
; __device__ __forceinline__ void mem_unit(const MemArgs& A, int unit, char* lds, int wv) {
;     ...
;     if (hi == 0) wsl[r32] = l_reg;
;     asm volatile("s_waitcnt lgkmcnt(0)" ::: "memory");
; #pragma unroll
;     for (int r = 0; r < 16; ++r) { const int rr_ = crow(r, hi); const float rl = 1.0f / wsl[rr_];
;         const bf16* gp = A.proj + (grow0 + rr_) * INC + C_MG + hm * 128 + r32; bf16* yp = A.y + (grow0 + rr_) * DM + Y_M + hm * 128 + r32;
; #pragma unroll
;         for (int d0 = 0; d0 < 4; ++d0) { const float g = bf2f(gp[d0 * 32]); const float val = o[d0][r] * rl * silu(g);
;             yp[d0 * 32] = (bf16)(cvtpk(val, val) & 0xffffu); } }
;     __syncthreads();
	v_mov_b32_e32 v16, v91
	s_nop 0
	v_lshlrev_b32_e32 v16, 16, v16
	v_mul_f32_e32 v1, 0xbfb8aa3b, v16
	v_exp_f32_e32 v1, v1
	s_nop 0
	v_add_f32_e32 v1, 1.0, v1
	v_div_scale_f32 v17, s[0:1], v1, v1, v16
	v_rcp_f32_e32 v32, v17
	s_nop 0
	v_fma_f32 v33, -v17, v32, 1.0
	v_fmac_f32_e32 v32, v33, v32
	v_div_scale_f32 v33, vcc, v16, v1, v16
	v_mul_f32_e32 v48, v33, v32
	v_fma_f32 v49, -v17, v48, v33
	v_fmac_f32_e32 v48, v49, v32
	v_fma_f32 v17, -v17, v48, v33
	v_div_fmas_f32 v17, v17, v32, v48
	v_div_fixup_f32 v1, v17, v1, v16
	v_mul_f32_e32 v0, v0, v1
	v_cvt_pk_bf16_f32 v0, v0, s0
	global_store_short v[64:65], v0, off offset:3264
	v_div_scale_f32 v0, s[0:1], v66, v66, 1.0
	v_rcp_f32_e32 v1, v0
	s_nop 0
	v_fma_f32 v16, -v0, v1, 1.0
	v_fmac_f32_e32 v1, v16, v1
	v_div_scale_f32 v16, vcc, 1.0, v66, 1.0
	v_mul_f32_e32 v17, v16, v1
	v_fma_f32 v32, -v0, v17, v16
	v_fmac_f32_e32 v17, v32, v1
	v_fma_f32 v0, -v0, v17, v16
	v_div_fmas_f32 v0, v0, v1, v17
	v_div_fixup_f32 v48, v0, v66, 1.0
	v_or_b32_e32 v0, 2, v68
	v_mad_u64_u32 v[16:17], s[0:1], v0, s33, v[70:71]
	v_add_u32_e32 v17, s6, v17
	v_lshl_add_u64 v[16:17], v[16:17], 0, s[84:85]
	v_lshl_add_u64 v[16:17], v[16:17], 0, v[176:177]
	v_lshl_add_u64 v[32:33], v[16:17], 0, s[2:3]
	v_add_co_u32_e32 v16, vcc, s63, v16
	v_mov_b32_e32 v1, v69
	s_nop 0
	v_addc_co_u32_e32 v17, vcc, 0, v17, vcc
	s_waitcnt vmcnt(28)
	v_mov_b32_e32 v16, v92
	v_mul_f32_e32 v17, v50, v48
	v_lshlrev_b64 v[0:1], 12, v[0:1]
	v_lshl_add_u64 v[0:1], s[82:83], 0, v[0:1]
	v_lshl_add_u64 v[0:1], v[0:1], 0, s[84:85]
	v_lshl_add_u64 v[0:1], v[0:1], 0, v[176:177]
	v_mul_f32_e32 v2, v2, v48
	s_nop 0
	v_lshlrev_b32_e32 v16, 16, v16
	v_mul_f32_e32 v49, 0xbfb8aa3b, v16
	v_exp_f32_e32 v49, v49
	s_nop 0
	v_add_f32_e32 v49, 1.0, v49
	v_div_scale_f32 v50, s[0:1], v49, v49, v16
	v_rcp_f32_e32 v64, v50
	s_nop 0
	v_fma_f32 v65, -v50, v64, 1.0
	v_fmac_f32_e32 v64, v65, v64
	v_div_scale_f32 v65, vcc, v16, v49, v16
	v_mul_f32_e32 v66, v65, v64
	v_fma_f32 v73, -v50, v66, v65
	v_fmac_f32_e32 v66, v73, v64
	v_fma_f32 v50, -v50, v66, v65
	v_div_fmas_f32 v50, v50, v64, v66
	v_div_fixup_f32 v16, v50, v49, v16
	v_mul_f32_e32 v16, v17, v16
	v_cvt_pk_bf16_f32 v16, v16, s0
	global_store_short v[0:1], v16, off offset:3072
	s_waitcnt vmcnt(28)
	v_mov_b32_e32 v16, v93
	v_mul_f32_e32 v17, v34, v48
	s_nop 0
	v_lshlrev_b32_e32 v16, 16, v16
	v_mul_f32_e32 v34, 0xbfb8aa3b, v16
	v_exp_f32_e32 v34, v34
	s_nop 0
	v_add_f32_e32 v34, 1.0, v34
	v_div_scale_f32 v49, s[0:1], v34, v34, v16
	v_rcp_f32_e32 v50, v49
	s_nop 0
	v_fma_f32 v64, -v49, v50, 1.0
	v_fmac_f32_e32 v50, v64, v50
	v_div_scale_f32 v64, vcc, v16, v34, v16
	v_mul_f32_e32 v65, v64, v50
	v_fma_f32 v66, -v49, v65, v64
	v_fmac_f32_e32 v65, v66, v50
	v_fma_f32 v49, -v49, v65, v64
	v_div_fmas_f32 v49, v49, v50, v65
	v_div_fixup_f32 v16, v49, v34, v16
	v_mul_f32_e32 v16, v17, v16
	v_cvt_pk_bf16_f32 v16, v16, s0
	global_store_short v[0:1], v16, off offset:3136
	s_waitcnt vmcnt(28)
	v_mov_b32_e32 v16, v94
	v_mul_f32_e32 v17, v18, v48
	s_nop 0
	v_lshlrev_b32_e32 v16, 16, v16
	v_mul_f32_e32 v18, 0xbfb8aa3b, v16
	v_exp_f32_e32 v18, v18
	s_nop 0
	v_add_f32_e32 v18, 1.0, v18
	v_div_scale_f32 v34, s[0:1], v18, v18, v16
	v_rcp_f32_e32 v49, v34
	s_nop 0
	v_fma_f32 v50, -v34, v49, 1.0
	v_fmac_f32_e32 v49, v50, v49
	v_div_scale_f32 v50, vcc, v16, v18, v16
	v_mul_f32_e32 v64, v50, v49
	v_fma_f32 v65, -v34, v64, v50
	v_fmac_f32_e32 v64, v65, v49
	v_fma_f32 v34, -v34, v64, v50
	v_div_fmas_f32 v34, v34, v49, v64
	v_div_fixup_f32 v16, v34, v18, v16
	v_mul_f32_e32 v16, v17, v16
	v_cvt_pk_bf16_f32 v16, v16, s0
	global_store_short v[0:1], v16, off offset:3200
	s_waitcnt vmcnt(28)
	v_mov_b32_e32 v16, v95
	s_nop 0
	v_lshlrev_b32_e32 v16, 16, v16
	v_mul_f32_e32 v17, 0xbfb8aa3b, v16
	v_exp_f32_e32 v17, v17
	s_nop 0
	v_add_f32_e32 v17, 1.0, v17
	v_div_scale_f32 v18, s[0:1], v17, v17, v16
	v_rcp_f32_e32 v32, v18
	s_nop 0
	v_fma_f32 v33, -v18, v32, 1.0
	v_fmac_f32_e32 v32, v33, v32
	v_div_scale_f32 v33, vcc, v16, v17, v16
	v_mul_f32_e32 v34, v33, v32
	v_fma_f32 v48, -v18, v34, v33
	v_fmac_f32_e32 v34, v48, v32
	v_fma_f32 v18, -v18, v34, v33
	v_div_fmas_f32 v18, v18, v32, v34
	v_div_fixup_f32 v16, v18, v17, v16
	v_mul_f32_e32 v2, v2, v16
	v_cvt_pk_bf16_f32 v2, v2, s0
	global_store_short v[0:1], v2, off offset:3264
	v_div_scale_f32 v0, s[0:1], v67, v67, 1.0
	v_rcp_f32_e32 v1, v0
	s_nop 0
	v_fma_f32 v2, -v0, v1, 1.0
	v_fmac_f32_e32 v1, v2, v1
	v_div_scale_f32 v2, vcc, 1.0, v67, 1.0
	v_mul_f32_e32 v16, v2, v1
	v_fma_f32 v17, -v0, v16, v2
	v_fmac_f32_e32 v16, v17, v1
	v_fma_f32 v0, -v0, v16, v2
	v_div_fmas_f32 v0, v0, v1, v16
	v_div_fixup_f32 v2, v0, v67, 1.0
	v_or_b32_e32 v0, 3, v68
	v_mad_u64_u32 v[16:17], s[0:1], v0, s33, v[70:71]
	v_add_u32_e32 v17, s6, v17
	v_lshl_add_u64 v[16:17], v[16:17], 0, s[84:85]
	v_lshl_add_u64 v[16:17], v[16:17], 0, v[176:177]
	v_lshl_add_u64 v[32:33], v[16:17], 0, s[2:3]
	v_add_co_u32_e32 v16, vcc, s63, v16
	v_mov_b32_e32 v1, v69
	s_nop 0
	v_addc_co_u32_e32 v17, vcc, 0, v17, vcc
	s_waitcnt vmcnt(28)
	v_mov_b32_e32 v16, v96
	v_mul_f32_e32 v17, v51, v2
	v_lshlrev_b64 v[0:1], 12, v[0:1]
	v_lshl_add_u64 v[0:1], s[82:83], 0, v[0:1]
	v_lshl_add_u64 v[0:1], v[0:1], 0, s[84:85]
	v_lshl_add_u64 v[0:1], v[0:1], 0, v[176:177]
	s_nop 0
	v_lshlrev_b32_e32 v16, 16, v16
	v_mul_f32_e32 v18, 0xbfb8aa3b, v16
	v_exp_f32_e32 v18, v18
	s_nop 0
	v_add_f32_e32 v18, 1.0, v18
	v_div_scale_f32 v34, s[0:1], v18, v18, v16
	v_rcp_f32_e32 v48, v34
	s_nop 0
	v_fma_f32 v49, -v34, v48, 1.0
	v_fmac_f32_e32 v48, v49, v48
	v_div_scale_f32 v49, vcc, v16, v18, v16
	v_mul_f32_e32 v50, v49, v48
	v_fma_f32 v51, -v34, v50, v49
	v_fmac_f32_e32 v50, v51, v48
	v_fma_f32 v34, -v34, v50, v49
	v_div_fmas_f32 v34, v34, v48, v50
	v_div_fixup_f32 v16, v34, v18, v16
	v_mul_f32_e32 v16, v17, v16
	v_cvt_pk_bf16_f32 v16, v16, s0
	global_store_short v[0:1], v16, off offset:3072
	s_waitcnt vmcnt(28)
; __device__ __forceinline__ int crow(int r, int hi) { return (r & 3) + 8 * (r >> 2) + 4 * hi; }
; __device__ __forceinline__ unsigned cvtpk(float lo, float hi) { f32x2_t v = {lo, hi}; bf16x2_t b = __builtin_convertvector(v, bf16x2_t); return __builtin_bit_cast(unsigned, b); }
; __device__ __forceinline__ float bf2f(unsigned short h) { return __uint_as_float(((unsigned)h) << 16); }
; __device__ __forceinline__ float silu(float x) { return x / (1.0f + __expf(-x)); }
; __device__ __forceinline__ void mem_unit(const MemArgs& A, int unit, char* lds, int wv) {
;     ...
;     if (hi == 0) wsl[r32] = l_reg;
;     asm volatile("s_waitcnt lgkmcnt(0)" ::: "memory");
; #pragma unroll
;     for (int r = 0; r < 16; ++r) { const int rr_ = crow(r, hi); const float rl = 1.0f / wsl[rr_];
;         const bf16* gp = A.proj + (grow0 + rr_) * INC + C_MG + hm * 128 + r32; bf16* yp = A.y + (grow0 + rr_) * DM + Y_M + hm * 128 + r32;
; #pragma unroll
;         for (int d0 = 0; d0 < 4; ++d0) { const float g = bf2f(gp[d0 * 32]); const float val = o[d0][r] * rl * silu(g);
;             yp[d0 * 32] = (bf16)(cvtpk(val, val) & 0xffffu); } }
;     __syncthreads();
	v_mov_b32_e32 v16, v97
	v_mul_f32_e32 v17, v35, v2
	s_nop 0
	v_lshlrev_b32_e32 v16, 16, v16
	v_mul_f32_e32 v18, 0xbfb8aa3b, v16
	v_exp_f32_e32 v18, v18
	s_nop 0
	v_add_f32_e32 v18, 1.0, v18
	v_div_scale_f32 v34, s[0:1], v18, v18, v16
	v_rcp_f32_e32 v35, v34
	s_nop 0
	v_fma_f32 v48, -v34, v35, 1.0
	v_fmac_f32_e32 v35, v48, v35
	v_div_scale_f32 v48, vcc, v16, v18, v16
	v_mul_f32_e32 v49, v48, v35
	v_fma_f32 v50, -v34, v49, v48
	v_fmac_f32_e32 v49, v50, v35
	v_fma_f32 v34, -v34, v49, v48
	v_div_fmas_f32 v34, v34, v35, v49
	v_div_fixup_f32 v16, v34, v18, v16
	v_mul_f32_e32 v16, v17, v16
	v_cvt_pk_bf16_f32 v16, v16, s0
	global_store_short v[0:1], v16, off offset:3136
	s_waitcnt vmcnt(28)
	v_mov_b32_e32 v16, v98
	v_mul_f32_e32 v17, v19, v2
	v_mul_f32_e32 v2, v3, v2
	s_nop 0
	v_lshlrev_b32_e32 v16, 16, v16
	v_mul_f32_e32 v18, 0xbfb8aa3b, v16
	v_exp_f32_e32 v18, v18
	s_nop 0
	v_add_f32_e32 v18, 1.0, v18
	v_div_scale_f32 v19, s[0:1], v18, v18, v16
	v_rcp_f32_e32 v34, v19
	s_nop 0
	v_fma_f32 v35, -v19, v34, 1.0
	v_fmac_f32_e32 v34, v35, v34
	v_div_scale_f32 v35, vcc, v16, v18, v16
	v_mul_f32_e32 v48, v35, v34
	v_fma_f32 v49, -v19, v48, v35
	v_fmac_f32_e32 v48, v49, v34
	v_fma_f32 v19, -v19, v48, v35
	v_div_fmas_f32 v19, v19, v34, v48
	v_div_fixup_f32 v16, v19, v18, v16
	v_mul_f32_e32 v16, v17, v16
	v_cvt_pk_bf16_f32 v16, v16, s0
	global_store_short v[0:1], v16, off offset:3200
	s_waitcnt vmcnt(28)
	v_mov_b32_e32 v16, v99
	s_nop 0
	v_lshlrev_b32_e32 v16, 16, v16
	v_mul_f32_e32 v3, 0xbfb8aa3b, v16
	v_exp_f32_e32 v3, v3
	s_nop 0
	v_add_f32_e32 v3, 1.0, v3
	v_div_scale_f32 v17, s[0:1], v3, v3, v16
	v_rcp_f32_e32 v18, v17
	s_nop 0
	v_fma_f32 v19, -v17, v18, 1.0
	v_fmac_f32_e32 v18, v19, v18
	v_div_scale_f32 v19, vcc, v16, v3, v16
	v_mul_f32_e32 v32, v19, v18
	v_fma_f32 v33, -v17, v32, v19
	v_fmac_f32_e32 v32, v33, v18
	v_fma_f32 v17, -v17, v32, v19
	v_div_fmas_f32 v17, v17, v18, v32
	v_div_fixup_f32 v3, v17, v3, v16
	v_mul_f32_e32 v2, v2, v3
	v_cvt_pk_bf16_f32 v2, v2, s0
	global_store_short v[0:1], v2, off offset:3264
	ds_read_b128 v[0:3], v72 offset:32
	s_waitcnt lgkmcnt(0)
	v_div_scale_f32 v16, s[0:1], v0, v0, 1.0
	v_rcp_f32_e32 v17, v16
	s_nop 0
	v_fma_f32 v18, -v16, v17, 1.0
	v_fmac_f32_e32 v17, v18, v17
	v_div_scale_f32 v18, vcc, 1.0, v0, 1.0
	v_mul_f32_e32 v19, v18, v17
	v_fma_f32 v32, -v16, v19, v18
	v_fmac_f32_e32 v19, v32, v17
	v_fma_f32 v16, -v16, v19, v18
	v_div_fmas_f32 v16, v16, v17, v19
	v_div_fixup_f32 v0, v16, v0, 1.0
	v_or_b32_e32 v16, 8, v68
	v_mad_u64_u32 v[18:19], s[0:1], v16, s33, v[70:71]
	v_add_u32_e32 v19, s6, v19
	v_lshl_add_u64 v[18:19], v[18:19], 0, s[84:85]
	v_lshl_add_u64 v[32:33], v[18:19], 0, v[176:177]
	v_lshl_add_u64 v[18:19], v[32:33], 0, s[2:3]
	v_add_co_u32_e32 v32, vcc, s63, v32
	v_mov_b32_e32 v17, v69
	s_nop 0
	v_addc_co_u32_e32 v33, vcc, 0, v33, vcc
	s_waitcnt vmcnt(28)
	v_mov_b32_e32 v32, v100
	v_lshlrev_b64 v[16:17], 12, v[16:17]
	v_lshl_add_u64 v[16:17], s[82:83], 0, v[16:17]
	v_mul_f32_e32 v33, v52, v0
	v_lshl_add_u64 v[16:17], v[16:17], 0, s[84:85]
	v_lshl_add_u64 v[16:17], v[16:17], 0, v[176:177]
	v_mul_f32_e32 v20, v20, v0
	s_nop 0
	v_lshlrev_b32_e32 v32, 16, v32
	v_mul_f32_e32 v34, 0xbfb8aa3b, v32
	v_exp_f32_e32 v34, v34
	s_nop 0
	v_add_f32_e32 v34, 1.0, v34
	v_div_scale_f32 v35, s[0:1], v34, v34, v32
	v_rcp_f32_e32 v48, v35
	s_nop 0
	v_fma_f32 v49, -v35, v48, 1.0
	v_fmac_f32_e32 v48, v49, v48
	v_div_scale_f32 v49, vcc, v32, v34, v32
	v_mul_f32_e32 v50, v49, v48
	v_fma_f32 v51, -v35, v50, v49
	v_fmac_f32_e32 v50, v51, v48
	v_fma_f32 v35, -v35, v50, v49
	v_div_fmas_f32 v35, v35, v48, v50
	v_div_fixup_f32 v32, v35, v34, v32
	v_mul_f32_e32 v32, v33, v32
	v_cvt_pk_bf16_f32 v32, v32, s0
	global_store_short v[16:17], v32, off offset:3072
	s_waitcnt vmcnt(28)
	v_mov_b32_e32 v32, v101
	v_mul_f32_e32 v33, v36, v0
	v_mul_f32_e32 v0, v4, v0
	s_nop 0
	v_lshlrev_b32_e32 v32, 16, v32
	v_mul_f32_e32 v34, 0xbfb8aa3b, v32
	v_exp_f32_e32 v34, v34
	s_nop 0
	v_add_f32_e32 v34, 1.0, v34
	v_div_scale_f32 v35, s[0:1], v34, v34, v32
	v_rcp_f32_e32 v36, v35
	s_nop 0
	v_fma_f32 v48, -v35, v36, 1.0
	v_fmac_f32_e32 v36, v48, v36
	v_div_scale_f32 v48, vcc, v32, v34, v32
	v_mul_f32_e32 v49, v48, v36
	v_fma_f32 v50, -v35, v49, v48
	v_fmac_f32_e32 v49, v50, v36
	v_fma_f32 v35, -v35, v49, v48
	v_div_fmas_f32 v35, v35, v36, v49
	v_div_fixup_f32 v32, v35, v34, v32
	v_mul_f32_e32 v32, v33, v32
	v_cvt_pk_bf16_f32 v32, v32, s0
	global_store_short v[16:17], v32, off offset:3136
	s_waitcnt vmcnt(28)
	v_mov_b32_e32 v32, v102
	s_nop 0
	v_lshlrev_b32_e32 v32, 16, v32
	s_waitcnt vmcnt(28)
	v_mov_b32_e32 v18, v103
	v_mul_f32_e32 v33, 0xbfb8aa3b, v32
	v_exp_f32_e32 v33, v33
	s_nop 0
	v_lshlrev_b32_e32 v18, 16, v18
	v_add_f32_e32 v33, 1.0, v33
	v_div_scale_f32 v34, s[0:1], v33, v33, v32
	v_rcp_f32_e32 v35, v34
	v_mul_f32_e32 v4, 0xbfb8aa3b, v18
	v_exp_f32_e32 v4, v4
	v_fma_f32 v36, -v34, v35, 1.0
	v_fmac_f32_e32 v35, v36, v35
	v_div_scale_f32 v36, vcc, v32, v33, v32
	v_mul_f32_e32 v48, v36, v35
	v_fma_f32 v49, -v34, v48, v36
	v_fmac_f32_e32 v48, v49, v35
	v_fma_f32 v34, -v34, v48, v36
	v_div_fmas_f32 v34, v34, v35, v48
	v_div_fixup_f32 v32, v34, v33, v32
	v_mul_f32_e32 v20, v20, v32
	v_add_f32_e32 v4, 1.0, v4
	v_cvt_pk_bf16_f32 v20, v20, s0
	v_div_scale_f32 v19, s[0:1], v4, v4, v18
	global_store_short v[16:17], v20, off offset:3200
	v_rcp_f32_e32 v20, v19
	s_nop 0
	v_fma_f32 v32, -v19, v20, 1.0
	v_fmac_f32_e32 v20, v32, v20
	v_div_scale_f32 v32, vcc, v18, v4, v18
	v_mul_f32_e32 v33, v32, v20
	v_fma_f32 v34, -v19, v33, v32
	v_fmac_f32_e32 v33, v34, v20
	v_fma_f32 v19, -v19, v33, v32
	v_div_fmas_f32 v19, v19, v20, v33
	v_div_fixup_f32 v4, v19, v4, v18
	v_mul_f32_e32 v0, v0, v4
	v_cvt_pk_bf16_f32 v0, v0, s0
	global_store_short v[16:17], v0, off offset:3264
	v_div_scale_f32 v0, s[0:1], v1, v1, 1.0
	v_rcp_f32_e32 v4, v0
	s_nop 0
	v_fma_f32 v16, -v0, v4, 1.0
	v_fmac_f32_e32 v4, v16, v4
	v_div_scale_f32 v16, vcc, 1.0, v1, 1.0
	v_mul_f32_e32 v17, v16, v4
	v_fma_f32 v18, -v0, v17, v16
	v_fmac_f32_e32 v17, v18, v4
	v_fma_f32 v0, -v0, v17, v16
	v_div_fmas_f32 v0, v0, v4, v17
	v_div_fixup_f32 v4, v0, v1, 1.0
	v_or_b32_e32 v0, 9, v68
	v_mad_u64_u32 v[16:17], s[0:1], v0, s33, v[70:71]
	v_add_u32_e32 v17, s6, v17
	v_lshl_add_u64 v[16:17], v[16:17], 0, s[84:85]
	v_lshl_add_u64 v[18:19], v[16:17], 0, v[176:177]
	v_lshl_add_u64 v[16:17], v[18:19], 0, s[2:3]
	v_add_co_u32_e32 v18, vcc, s63, v18
	v_mov_b32_e32 v1, v69
	s_nop 0
	v_addc_co_u32_e32 v19, vcc, 0, v19, vcc
	s_waitcnt vmcnt(28)
; __device__ __forceinline__ int crow(int r, int hi) { return (r & 3) + 8 * (r >> 2) + 4 * hi; }
; __device__ __forceinline__ unsigned cvtpk(float lo, float hi) { f32x2_t v = {lo, hi}; bf16x2_t b = __builtin_convertvector(v, bf16x2_t); return __builtin_bit_cast(unsigned, b); }
; __device__ __forceinline__ float bf2f(unsigned short h) { return __uint_as_float(((unsigned)h) << 16); }
; __device__ __forceinline__ float silu(float x) { return x / (1.0f + __expf(-x)); }
; __device__ __forceinline__ void mem_unit(const MemArgs& A, int unit, char* lds, int wv) {
;     ...
;     if (hi == 0) wsl[r32] = l_reg;
;     asm volatile("s_waitcnt lgkmcnt(0)" ::: "memory");
; #pragma unroll
;     for (int r = 0; r < 16; ++r) { const int rr_ = crow(r, hi); const float rl = 1.0f / wsl[rr_];
;         const bf16* gp = A.proj + (grow0 + rr_) * INC + C_MG + hm * 128 + r32; bf16* yp = A.y + (grow0 + rr_) * DM + Y_M + hm * 128 + r32;
; #pragma unroll
;         for (int d0 = 0; d0 < 4; ++d0) { const float g = bf2f(gp[d0 * 32]); const float val = o[d0][r] * rl * silu(g);
;             yp[d0 * 32] = (bf16)(cvtpk(val, val) & 0xffffu); } }
;     __syncthreads();
	v_mov_b32_e32 v18, v104
	v_lshlrev_b64 v[0:1], 12, v[0:1]
	v_lshl_add_u64 v[0:1], s[82:83], 0, v[0:1]
	v_mul_f32_e32 v19, v53, v4
	v_lshl_add_u64 v[0:1], v[0:1], 0, s[84:85]
	v_lshl_add_u64 v[0:1], v[0:1], 0, v[176:177]
	s_nop 0
	v_lshlrev_b32_e32 v18, 16, v18
	v_mul_f32_e32 v20, 0xbfb8aa3b, v18
	v_exp_f32_e32 v20, v20
	s_nop 0
	v_add_f32_e32 v20, 1.0, v20
	v_div_scale_f32 v32, s[0:1], v20, v20, v18
	v_rcp_f32_e32 v33, v32
	s_nop 0
	v_fma_f32 v34, -v32, v33, 1.0
	v_fmac_f32_e32 v33, v34, v33
	v_div_scale_f32 v34, vcc, v18, v20, v18
	v_mul_f32_e32 v35, v34, v33
	v_fma_f32 v36, -v32, v35, v34
	v_fmac_f32_e32 v35, v36, v33
	v_fma_f32 v32, -v32, v35, v34
	v_div_fmas_f32 v32, v32, v33, v35
	v_div_fixup_f32 v18, v32, v20, v18
	v_mul_f32_e32 v18, v19, v18
	v_cvt_pk_bf16_f32 v18, v18, s0
	global_store_short v[0:1], v18, off offset:3072
	s_waitcnt vmcnt(28)
	v_mov_b32_e32 v18, v105
	v_mul_f32_e32 v19, v37, v4
	s_nop 0
	v_lshlrev_b32_e32 v18, 16, v18
	v_mul_f32_e32 v20, 0xbfb8aa3b, v18
	v_exp_f32_e32 v20, v20
	s_nop 0
	v_add_f32_e32 v20, 1.0, v20
	v_div_scale_f32 v32, s[0:1], v20, v20, v18
	v_rcp_f32_e32 v33, v32
	s_nop 0
	v_fma_f32 v34, -v32, v33, 1.0
	v_fmac_f32_e32 v33, v34, v33
	v_div_scale_f32 v34, vcc, v18, v20, v18
	v_mul_f32_e32 v35, v34, v33
	v_fma_f32 v36, -v32, v35, v34
	v_fmac_f32_e32 v35, v36, v33
	v_fma_f32 v32, -v32, v35, v34
	v_div_fmas_f32 v32, v32, v33, v35
	v_div_fixup_f32 v18, v32, v20, v18
	v_mul_f32_e32 v18, v19, v18
	v_cvt_pk_bf16_f32 v18, v18, s0
	global_store_short v[0:1], v18, off offset:3136
	s_waitcnt vmcnt(28)
	v_mov_b32_e32 v18, v106
	v_mul_f32_e32 v19, v21, v4
	s_waitcnt vmcnt(28)
	v_mov_b32_e32 v16, v107
	v_mul_f32_e32 v4, v5, v4
	s_nop 0
	v_lshlrev_b32_e32 v18, 16, v18
	v_mul_f32_e32 v20, 0xbfb8aa3b, v18
	v_exp_f32_e32 v20, v20
	s_nop 0
	v_lshlrev_b32_e32 v16, 16, v16
	v_mul_f32_e32 v5, 0xbfb8aa3b, v16
	v_exp_f32_e32 v5, v5
	v_add_f32_e32 v20, 1.0, v20
	v_div_scale_f32 v21, s[0:1], v20, v20, v18
	v_rcp_f32_e32 v32, v21
	v_add_f32_e32 v5, 1.0, v5
	v_fma_f32 v33, -v21, v32, 1.0
	v_fmac_f32_e32 v32, v33, v32
	v_div_scale_f32 v33, vcc, v18, v20, v18
	v_mul_f32_e32 v34, v33, v32
	v_fma_f32 v35, -v21, v34, v33
	v_fmac_f32_e32 v34, v35, v32
	v_fma_f32 v21, -v21, v34, v33
	v_div_fmas_f32 v21, v21, v32, v34
	v_div_fixup_f32 v18, v21, v20, v18
	v_mul_f32_e32 v18, v19, v18
	v_cvt_pk_bf16_f32 v18, v18, s0
	v_div_scale_f32 v17, s[0:1], v5, v5, v16
	global_store_short v[0:1], v18, off offset:3200
	v_rcp_f32_e32 v18, v17
	s_nop 0
	v_fma_f32 v19, -v17, v18, 1.0
	v_fmac_f32_e32 v18, v19, v18
	v_div_scale_f32 v19, vcc, v16, v5, v16
	v_mul_f32_e32 v20, v19, v18
	v_fma_f32 v21, -v17, v20, v19
	v_fmac_f32_e32 v20, v21, v18
	v_fma_f32 v17, -v17, v20, v19
	v_div_fmas_f32 v17, v17, v18, v20
	v_div_fixup_f32 v5, v17, v5, v16
	v_mul_f32_e32 v4, v4, v5
	v_cvt_pk_bf16_f32 v4, v4, s0
	global_store_short v[0:1], v4, off offset:3264
	v_div_scale_f32 v0, s[0:1], v2, v2, 1.0
	v_rcp_f32_e32 v1, v0
	s_nop 0
	v_fma_f32 v4, -v0, v1, 1.0
	v_fmac_f32_e32 v1, v4, v1
	v_div_scale_f32 v4, vcc, 1.0, v2, 1.0
	v_mul_f32_e32 v5, v4, v1
	v_fma_f32 v16, -v0, v5, v4
	v_fmac_f32_e32 v5, v16, v1
	v_fma_f32 v0, -v0, v5, v4
	v_div_fmas_f32 v0, v0, v1, v5
	v_div_fixup_f32 v2, v0, v2, 1.0
	v_or_b32_e32 v0, 10, v68
	v_mad_u64_u32 v[4:5], s[0:1], v0, s33, v[70:71]
	v_add_u32_e32 v5, s6, v5
	v_lshl_add_u64 v[4:5], v[4:5], 0, s[84:85]
	v_lshl_add_u64 v[16:17], v[4:5], 0, v[176:177]
	v_lshl_add_u64 v[4:5], v[16:17], 0, s[2:3]
	v_add_co_u32_e32 v16, vcc, s63, v16
	v_mov_b32_e32 v1, v69
	s_nop 0
	v_addc_co_u32_e32 v17, vcc, 0, v17, vcc
	s_waitcnt vmcnt(28)
	v_mov_b32_e32 v16, v108
	v_lshlrev_b64 v[0:1], 12, v[0:1]
	v_lshl_add_u64 v[0:1], s[82:83], 0, v[0:1]
	v_mul_f32_e32 v17, v54, v2
	v_lshl_add_u64 v[0:1], v[0:1], 0, s[84:85]
	v_lshl_add_u64 v[0:1], v[0:1], 0, v[176:177]
	s_nop 0
	v_lshlrev_b32_e32 v16, 16, v16
	v_mul_f32_e32 v18, 0xbfb8aa3b, v16
	v_exp_f32_e32 v18, v18
	s_nop 0
	v_add_f32_e32 v18, 1.0, v18
	v_div_scale_f32 v19, s[0:1], v18, v18, v16
	v_rcp_f32_e32 v20, v19
	s_nop 0
	v_fma_f32 v21, -v19, v20, 1.0
	v_fmac_f32_e32 v20, v21, v20
	v_div_scale_f32 v21, vcc, v16, v18, v16
	v_mul_f32_e32 v32, v21, v20
	v_fma_f32 v33, -v19, v32, v21
	v_fmac_f32_e32 v32, v33, v20
	v_fma_f32 v19, -v19, v32, v21
	v_div_fmas_f32 v19, v19, v20, v32
	v_div_fixup_f32 v16, v19, v18, v16
	v_mul_f32_e32 v16, v17, v16
	v_cvt_pk_bf16_f32 v16, v16, s0
	global_store_short v[0:1], v16, off offset:3072
	s_waitcnt vmcnt(28)
	v_mov_b32_e32 v16, v109
	v_mul_f32_e32 v17, v38, v2
	s_nop 0
	v_lshlrev_b32_e32 v16, 16, v16
	v_mul_f32_e32 v18, 0xbfb8aa3b, v16
	v_exp_f32_e32 v18, v18
	s_nop 0
	v_add_f32_e32 v18, 1.0, v18
	v_div_scale_f32 v19, s[0:1], v18, v18, v16
	v_rcp_f32_e32 v20, v19
	s_nop 0
	v_fma_f32 v21, -v19, v20, 1.0
	v_fmac_f32_e32 v20, v21, v20
	v_div_scale_f32 v21, vcc, v16, v18, v16
	v_mul_f32_e32 v32, v21, v20
	v_fma_f32 v33, -v19, v32, v21
	v_fmac_f32_e32 v32, v33, v20
	v_fma_f32 v19, -v19, v32, v21
	v_div_fmas_f32 v19, v19, v20, v32
	v_div_fixup_f32 v16, v19, v18, v16
	v_mul_f32_e32 v16, v17, v16
	v_cvt_pk_bf16_f32 v16, v16, s0
	global_store_short v[0:1], v16, off offset:3136
	s_waitcnt vmcnt(28)
	v_mov_b32_e32 v16, v110
	v_mul_f32_e32 v17, v22, v2
	s_waitcnt vmcnt(28)
; __device__ __forceinline__ int crow(int r, int hi) { return (r & 3) + 8 * (r >> 2) + 4 * hi; }
; __device__ __forceinline__ unsigned cvtpk(float lo, float hi) { f32x2_t v = {lo, hi}; bf16x2_t b = __builtin_convertvector(v, bf16x2_t); return __builtin_bit_cast(unsigned, b); }
; __device__ __forceinline__ float bf2f(unsigned short h) { return __uint_as_float(((unsigned)h) << 16); }
; __device__ __forceinline__ float silu(float x) { return x / (1.0f + __expf(-x)); }
; __device__ __forceinline__ void mem_unit(const MemArgs& A, int unit, char* lds, int wv) {
;     ...
;     if (hi == 0) wsl[r32] = l_reg;
;     asm volatile("s_waitcnt lgkmcnt(0)" ::: "memory");
; #pragma unroll
;     for (int r = 0; r < 16; ++r) { const int rr_ = crow(r, hi); const float rl = 1.0f / wsl[rr_];
;         const bf16* gp = A.proj + (grow0 + rr_) * INC + C_MG + hm * 128 + r32; bf16* yp = A.y + (grow0 + rr_) * DM + Y_M + hm * 128 + r32;
; #pragma unroll
;         for (int d0 = 0; d0 < 4; ++d0) { const float g = bf2f(gp[d0 * 32]); const float val = o[d0][r] * rl * silu(g);
;             yp[d0 * 32] = (bf16)(cvtpk(val, val) & 0xffffu); } }
;     __syncthreads();
	v_mov_b32_e32 v4, v111
	v_mul_f32_e32 v2, v6, v2
	s_nop 0
	v_lshlrev_b32_e32 v16, 16, v16
	v_mul_f32_e32 v18, 0xbfb8aa3b, v16
	v_exp_f32_e32 v18, v18
	s_nop 0
	v_lshlrev_b32_e32 v4, 16, v4
	v_mul_f32_e32 v5, 0xbfb8aa3b, v4
	v_exp_f32_e32 v5, v5
	v_add_f32_e32 v18, 1.0, v18
	v_div_scale_f32 v19, s[0:1], v18, v18, v16
	v_rcp_f32_e32 v20, v19
	v_add_f32_e32 v5, 1.0, v5
	v_fma_f32 v21, -v19, v20, 1.0
	v_fmac_f32_e32 v20, v21, v20
	v_div_scale_f32 v21, vcc, v16, v18, v16
	v_mul_f32_e32 v22, v21, v20
	v_fma_f32 v32, -v19, v22, v21
	v_fmac_f32_e32 v22, v32, v20
	v_fma_f32 v19, -v19, v22, v21
	v_div_fmas_f32 v19, v19, v20, v22
	v_div_fixup_f32 v16, v19, v18, v16
	v_mul_f32_e32 v16, v17, v16
	v_cvt_pk_bf16_f32 v16, v16, s0
	v_div_scale_f32 v6, s[0:1], v5, v5, v4
	global_store_short v[0:1], v16, off offset:3200
	v_rcp_f32_e32 v16, v6
	s_nop 0
	v_fma_f32 v17, -v6, v16, 1.0
	v_fmac_f32_e32 v16, v17, v16
	v_div_scale_f32 v17, vcc, v4, v5, v4
	v_mul_f32_e32 v18, v17, v16
	v_fma_f32 v19, -v6, v18, v17
	v_fmac_f32_e32 v18, v19, v16
	v_fma_f32 v6, -v6, v18, v17
	v_div_fmas_f32 v6, v6, v16, v18
	v_div_fixup_f32 v4, v6, v5, v4
	v_mul_f32_e32 v2, v2, v4
	v_cvt_pk_bf16_f32 v2, v2, s0
	global_store_short v[0:1], v2, off offset:3264
	v_div_scale_f32 v0, s[0:1], v3, v3, 1.0
	v_rcp_f32_e32 v1, v0
	s_nop 0
	v_fma_f32 v2, -v0, v1, 1.0
	v_fmac_f32_e32 v1, v2, v1
	v_div_scale_f32 v2, vcc, 1.0, v3, 1.0
	v_mul_f32_e32 v4, v2, v1
	v_fma_f32 v5, -v0, v4, v2
	v_fmac_f32_e32 v4, v5, v1
	v_fma_f32 v0, -v0, v4, v2
	v_div_fmas_f32 v0, v0, v1, v4
	v_div_fixup_f32 v4, v0, v3, 1.0
	v_or_b32_e32 v0, 11, v68
	v_mad_u64_u32 v[2:3], s[0:1], v0, s33, v[70:71]
	v_add_u32_e32 v3, s6, v3
	v_lshl_add_u64 v[2:3], v[2:3], 0, s[84:85]
	v_lshl_add_u64 v[16:17], v[2:3], 0, v[176:177]
	v_lshl_add_u64 v[2:3], v[16:17], 0, s[2:3]
	v_add_co_u32_e32 v16, vcc, s63, v16
	v_mov_b32_e32 v1, v69
	s_nop 0
	v_addc_co_u32_e32 v17, vcc, 0, v17, vcc
	s_waitcnt vmcnt(28)
	v_mov_b32_e32 v5, v157
	v_lshlrev_b64 v[0:1], 12, v[0:1]
	v_lshl_add_u64 v[0:1], s[82:83], 0, v[0:1]
	v_mul_f32_e32 v6, v55, v4
	v_lshl_add_u64 v[0:1], v[0:1], 0, s[84:85]
	v_lshl_add_u64 v[0:1], v[0:1], 0, v[176:177]
	s_nop 0
	v_lshlrev_b32_e32 v5, 16, v5
	v_mul_f32_e32 v16, 0xbfb8aa3b, v5
	v_exp_f32_e32 v16, v16
	s_nop 0
	v_add_f32_e32 v16, 1.0, v16
	v_div_scale_f32 v17, s[0:1], v16, v16, v5
	v_rcp_f32_e32 v18, v17
	s_nop 0
	v_fma_f32 v19, -v17, v18, 1.0
	v_fmac_f32_e32 v18, v19, v18
	v_div_scale_f32 v19, vcc, v5, v16, v5
	v_mul_f32_e32 v20, v19, v18
	v_fma_f32 v21, -v17, v20, v19
	v_fmac_f32_e32 v20, v21, v18
	v_fma_f32 v17, -v17, v20, v19
	v_div_fmas_f32 v17, v17, v18, v20
	v_div_fixup_f32 v5, v17, v16, v5
	v_mul_f32_e32 v5, v6, v5
	v_cvt_pk_bf16_f32 v5, v5, s0
	global_store_short v[0:1], v5, off offset:3072
	s_waitcnt vmcnt(28)
	v_mov_b32_e32 v5, v158
	v_mul_f32_e32 v6, v39, v4
	s_nop 0
	v_lshlrev_b32_e32 v5, 16, v5
	v_mul_f32_e32 v16, 0xbfb8aa3b, v5
	v_exp_f32_e32 v16, v16
	s_nop 0
	v_add_f32_e32 v16, 1.0, v16
	v_div_scale_f32 v17, s[0:1], v16, v16, v5
	v_rcp_f32_e32 v18, v17
	s_nop 0
	v_fma_f32 v19, -v17, v18, 1.0
	v_fmac_f32_e32 v18, v19, v18
	v_div_scale_f32 v19, vcc, v5, v16, v5
	v_mul_f32_e32 v20, v19, v18
	v_fma_f32 v21, -v17, v20, v19
	v_fmac_f32_e32 v20, v21, v18
	v_fma_f32 v17, -v17, v20, v19
	v_div_fmas_f32 v17, v17, v18, v20
	v_div_fixup_f32 v5, v17, v16, v5
	v_mul_f32_e32 v5, v6, v5
	v_cvt_pk_bf16_f32 v5, v5, s0
	global_store_short v[0:1], v5, off offset:3136
	s_waitcnt vmcnt(28)
	v_mov_b32_e32 v5, v159
	v_mul_f32_e32 v6, v23, v4
	s_waitcnt vmcnt(28)
	v_mov_b32_e32 v2, v160
	v_mul_f32_e32 v3, v7, v4
	s_nop 0
	v_lshlrev_b32_e32 v5, 16, v5
	v_mul_f32_e32 v16, 0xbfb8aa3b, v5
	v_exp_f32_e32 v16, v16
	s_nop 0
	v_lshlrev_b32_e32 v2, 16, v2
	v_mul_f32_e32 v4, 0xbfb8aa3b, v2
	v_exp_f32_e32 v4, v4
	v_add_f32_e32 v16, 1.0, v16
	v_div_scale_f32 v17, s[0:1], v16, v16, v5
	v_rcp_f32_e32 v18, v17
	v_add_f32_e32 v4, 1.0, v4
	v_fma_f32 v19, -v17, v18, 1.0
	v_fmac_f32_e32 v18, v19, v18
	v_div_scale_f32 v19, vcc, v5, v16, v5
	v_mul_f32_e32 v20, v19, v18
	v_fma_f32 v21, -v17, v20, v19
	v_fmac_f32_e32 v20, v21, v18
	v_fma_f32 v17, -v17, v20, v19
	v_div_fmas_f32 v17, v17, v18, v20
	v_div_fixup_f32 v5, v17, v16, v5
	v_mul_f32_e32 v5, v6, v5
	v_cvt_pk_bf16_f32 v5, v5, s0
	global_store_short v[0:1], v5, off offset:3200
	v_div_scale_f32 v5, s[0:1], v4, v4, v2
	v_rcp_f32_e32 v6, v5
	s_nop 0
	v_fma_f32 v7, -v5, v6, 1.0
	v_fmac_f32_e32 v6, v7, v6
	v_div_scale_f32 v7, vcc, v2, v4, v2
	v_mul_f32_e32 v16, v7, v6
	v_fma_f32 v17, -v5, v16, v7
	v_fmac_f32_e32 v16, v17, v6
	v_fma_f32 v5, -v5, v16, v7
	v_div_fmas_f32 v5, v5, v6, v16
	v_div_fixup_f32 v2, v5, v4, v2
	v_mul_f32_e32 v2, v3, v2
	v_cvt_pk_bf16_f32 v2, v2, s0
	global_store_short v[0:1], v2, off offset:3264
	s_waitcnt vmcnt(16)
; __device__ __forceinline__ int crow(int r, int hi) { return (r & 3) + 8 * (r >> 2) + 4 * hi; }
; __device__ __forceinline__ unsigned cvtpk(float lo, float hi) { f32x2_t v = {lo, hi}; bf16x2_t b = __builtin_convertvector(v, bf16x2_t); return __builtin_bit_cast(unsigned, b); }
; __device__ __forceinline__ float bf2f(unsigned short h) { return __uint_as_float(((unsigned)h) << 16); }
; __device__ __forceinline__ float silu(float x) { return x / (1.0f + __expf(-x)); }
; __device__ __forceinline__ void mem_unit(const MemArgs& A, int unit, char* lds, int wv) {
;     ...
;     if (hi == 0) wsl[r32] = l_reg;
;     asm volatile("s_waitcnt lgkmcnt(0)" ::: "memory");
; #pragma unroll
;     for (int r = 0; r < 16; ++r) { const int rr_ = crow(r, hi); const float rl = 1.0f / wsl[rr_];
;         const bf16* gp = A.proj + (grow0 + rr_) * INC + C_MG + hm * 128 + r32; bf16* yp = A.y + (grow0 + rr_) * DM + Y_M + hm * 128 + r32;
; #pragma unroll
;         for (int d0 = 0; d0 < 4; ++d0) { const float g = bf2f(gp[d0 * 32]); const float val = o[d0][r] * rl * silu(g);
;             yp[d0 * 32] = (bf16)(cvtpk(val, val) & 0xffffu); } }
;     __syncthreads();
	v_add_u32_e32 v162, 0x38000, v161
	global_load_ushort v84, v162, s[80:81]
	global_load_ushort v85, v162, s[80:81] offset:64
	global_load_ushort v86, v162, s[80:81] offset:128
	global_load_ushort v87, v162, s[80:81] offset:192
	v_add_u32_e32 v163, 0x3b800, v161
	global_load_ushort v88, v163, s[80:81]
	global_load_ushort v89, v163, s[80:81] offset:64
	global_load_ushort v90, v163, s[80:81] offset:128
	global_load_ushort v91, v163, s[80:81] offset:192
	v_add_u32_e32 v162, 0x3f000, v161
	global_load_ushort v92, v162, s[80:81]
	global_load_ushort v93, v162, s[80:81] offset:64
	global_load_ushort v94, v162, s[80:81] offset:128
	global_load_ushort v95, v162, s[80:81] offset:192
	v_add_u32_e32 v163, 0x42800, v161
	global_load_ushort v96, v163, s[80:81]
	global_load_ushort v97, v163, s[80:81] offset:64
	global_load_ushort v98, v163, s[80:81] offset:128
	global_load_ushort v99, v163, s[80:81] offset:192
	v_add_u32_e32 v162, 0x54000, v161
	global_load_ushort v100, v162, s[80:81]
	global_load_ushort v101, v162, s[80:81] offset:64
	global_load_ushort v102, v162, s[80:81] offset:128
	global_load_ushort v103, v162, s[80:81] offset:192
	v_add_u32_e32 v163, 0x57800, v161
	global_load_ushort v104, v163, s[80:81]
	global_load_ushort v105, v163, s[80:81] offset:64
	global_load_ushort v106, v163, s[80:81] offset:128
	global_load_ushort v107, v163, s[80:81] offset:192
	v_add_u32_e32 v162, 0x5b000, v161
	global_load_ushort v108, v162, s[80:81]
	global_load_ushort v109, v162, s[80:81] offset:64
	global_load_ushort v110, v162, s[80:81] offset:128
	global_load_ushort v111, v162, s[80:81] offset:192
	v_add_u32_e32 v163, 0x5e800, v161
	global_load_ushort v157, v163, s[80:81]
	global_load_ushort v158, v163, s[80:81] offset:64
	global_load_ushort v159, v163, s[80:81] offset:128
	global_load_ushort v160, v163, s[80:81] offset:192
	ds_read_b128 v[0:3], v72 offset:64
	s_waitcnt lgkmcnt(0)
	v_div_scale_f32 v4, s[0:1], v0, v0, 1.0
	v_rcp_f32_e32 v5, v4
	s_nop 0
	v_fma_f32 v6, -v4, v5, 1.0
	v_fmac_f32_e32 v5, v6, v5
	v_div_scale_f32 v6, vcc, 1.0, v0, 1.0
	v_mul_f32_e32 v7, v6, v5
	v_fma_f32 v16, -v4, v7, v6
	v_fmac_f32_e32 v7, v16, v5
	v_fma_f32 v4, -v4, v7, v6
	v_div_fmas_f32 v4, v4, v5, v7
	v_div_fixup_f32 v0, v4, v0, 1.0
	v_or_b32_e32 v4, 16, v68
	v_mad_u64_u32 v[6:7], s[0:1], v4, s33, v[70:71]
	v_add_u32_e32 v7, s6, v7
	v_lshl_add_u64 v[6:7], v[6:7], 0, s[84:85]
	v_lshl_add_u64 v[16:17], v[6:7], 0, v[176:177]
	v_lshl_add_u64 v[6:7], v[16:17], 0, s[2:3]
	v_add_co_u32_e32 v16, vcc, s63, v16
	v_mov_b32_e32 v5, v69
	s_nop 0
	v_addc_co_u32_e32 v17, vcc, 0, v17, vcc
	s_waitcnt vmcnt(28)
	v_mov_b32_e32 v16, v84
	v_lshlrev_b64 v[4:5], 12, v[4:5]
	v_lshl_add_u64 v[4:5], s[82:83], 0, v[4:5]
	v_mul_f32_e32 v17, v56, v0
	v_lshl_add_u64 v[4:5], v[4:5], 0, s[84:85]
	v_lshl_add_u64 v[4:5], v[4:5], 0, v[176:177]
	s_nop 0
	v_lshlrev_b32_e32 v16, 16, v16
	v_mul_f32_e32 v18, 0xbfb8aa3b, v16
	v_exp_f32_e32 v18, v18
	s_nop 0
	v_add_f32_e32 v18, 1.0, v18
	v_div_scale_f32 v19, s[0:1], v18, v18, v16
	v_rcp_f32_e32 v20, v19
	s_nop 0
	v_fma_f32 v21, -v19, v20, 1.0
	v_fmac_f32_e32 v20, v21, v20
	v_div_scale_f32 v21, vcc, v16, v18, v16
	v_mul_f32_e32 v22, v21, v20
	v_fma_f32 v23, -v19, v22, v21
	v_fmac_f32_e32 v22, v23, v20
	v_fma_f32 v19, -v19, v22, v21
	v_div_fmas_f32 v19, v19, v20, v22
	v_div_fixup_f32 v16, v19, v18, v16
	v_mul_f32_e32 v16, v17, v16
	v_cvt_pk_bf16_f32 v16, v16, s0
	global_store_short v[4:5], v16, off offset:3072
	s_waitcnt vmcnt(28)
	v_mov_b32_e32 v16, v85
	v_mul_f32_e32 v17, v40, v0
	s_nop 0
	v_lshlrev_b32_e32 v16, 16, v16
	v_mul_f32_e32 v18, 0xbfb8aa3b, v16
	v_exp_f32_e32 v18, v18
	s_nop 0
	v_add_f32_e32 v18, 1.0, v18
	v_div_scale_f32 v19, s[0:1], v18, v18, v16
	v_rcp_f32_e32 v20, v19
	s_nop 0
	v_fma_f32 v21, -v19, v20, 1.0
	v_fmac_f32_e32 v20, v21, v20
	v_div_scale_f32 v21, vcc, v16, v18, v16
	v_mul_f32_e32 v22, v21, v20
	v_fma_f32 v23, -v19, v22, v21
	v_fmac_f32_e32 v22, v23, v20
	v_fma_f32 v19, -v19, v22, v21
	v_div_fmas_f32 v19, v19, v20, v22
	v_div_fixup_f32 v16, v19, v18, v16
	v_mul_f32_e32 v16, v17, v16
	v_cvt_pk_bf16_f32 v16, v16, s0
	global_store_short v[4:5], v16, off offset:3136
	s_waitcnt vmcnt(28)
	v_mov_b32_e32 v16, v86
	v_mul_f32_e32 v17, v24, v0
	s_waitcnt vmcnt(28)
	v_mov_b32_e32 v6, v87
	v_mul_f32_e32 v0, v8, v0
	s_nop 0
	v_lshlrev_b32_e32 v16, 16, v16
	v_mul_f32_e32 v18, 0xbfb8aa3b, v16
	v_exp_f32_e32 v18, v18
	s_nop 0
	v_lshlrev_b32_e32 v6, 16, v6
	v_mul_f32_e32 v7, 0xbfb8aa3b, v6
	v_exp_f32_e32 v7, v7
	v_add_f32_e32 v18, 1.0, v18
	v_div_scale_f32 v19, s[0:1], v18, v18, v16
	v_rcp_f32_e32 v20, v19
	v_add_f32_e32 v7, 1.0, v7
	v_fma_f32 v21, -v19, v20, 1.0
	v_fmac_f32_e32 v20, v21, v20
	v_div_scale_f32 v21, vcc, v16, v18, v16
	v_mul_f32_e32 v22, v21, v20
	v_fma_f32 v23, -v19, v22, v21
	v_fmac_f32_e32 v22, v23, v20
	v_fma_f32 v19, -v19, v22, v21
	v_div_fmas_f32 v19, v19, v20, v22
	v_div_fixup_f32 v16, v19, v18, v16
	v_mul_f32_e32 v16, v17, v16
	v_cvt_pk_bf16_f32 v16, v16, s0
	v_div_scale_f32 v8, s[0:1], v7, v7, v6
	global_store_short v[4:5], v16, off offset:3200
	v_rcp_f32_e32 v16, v8
	s_nop 0
	v_fma_f32 v17, -v8, v16, 1.0
	v_fmac_f32_e32 v16, v17, v16
	v_div_scale_f32 v17, vcc, v6, v7, v6
	v_mul_f32_e32 v18, v17, v16
	v_fma_f32 v19, -v8, v18, v17
	v_fmac_f32_e32 v18, v19, v16
	v_fma_f32 v8, -v8, v18, v17
	v_div_fmas_f32 v8, v8, v16, v18
	v_div_fixup_f32 v6, v8, v7, v6
	v_mul_f32_e32 v0, v0, v6
	v_cvt_pk_bf16_f32 v0, v0, s0
	global_store_short v[4:5], v0, off offset:3264
	v_div_scale_f32 v0, s[0:1], v1, v1, 1.0
	v_rcp_f32_e32 v4, v0
	s_nop 0
	v_fma_f32 v5, -v0, v4, 1.0
	v_fmac_f32_e32 v4, v5, v4
	v_div_scale_f32 v5, vcc, 1.0, v1, 1.0
	v_mul_f32_e32 v6, v5, v4
	v_fma_f32 v7, -v0, v6, v5
	v_fmac_f32_e32 v6, v7, v4
	v_fma_f32 v0, -v0, v6, v5
	v_div_fmas_f32 v0, v0, v4, v6
	v_div_fixup_f32 v8, v0, v1, 1.0
	v_or_b32_e32 v0, 17, v68
	v_mad_u64_u32 v[4:5], s[0:1], v0, s33, v[70:71]
	v_add_u32_e32 v5, s6, v5
	v_lshl_add_u64 v[4:5], v[4:5], 0, s[84:85]
	v_lshl_add_u64 v[4:5], v[4:5], 0, v[176:177]
	v_lshl_add_u64 v[6:7], v[4:5], 0, s[2:3]
	v_add_co_u32_e32 v4, vcc, s63, v4
	v_mov_b32_e32 v1, v69
	s_nop 0
	v_addc_co_u32_e32 v5, vcc, 0, v5, vcc
	s_waitcnt vmcnt(28)
; __device__ __forceinline__ int crow(int r, int hi) { return (r & 3) + 8 * (r >> 2) + 4 * hi; }
; __device__ __forceinline__ unsigned cvtpk(float lo, float hi) { f32x2_t v = {lo, hi}; bf16x2_t b = __builtin_convertvector(v, bf16x2_t); return __builtin_bit_cast(unsigned, b); }
; __device__ __forceinline__ float bf2f(unsigned short h) { return __uint_as_float(((unsigned)h) << 16); }
; __device__ __forceinline__ float silu(float x) { return x / (1.0f + __expf(-x)); }
; __device__ __forceinline__ void mem_unit(const MemArgs& A, int unit, char* lds, int wv) {
;     ...
;     if (hi == 0) wsl[r32] = l_reg;
;     asm volatile("s_waitcnt lgkmcnt(0)" ::: "memory");
; #pragma unroll
;     for (int r = 0; r < 16; ++r) { const int rr_ = crow(r, hi); const float rl = 1.0f / wsl[rr_];
;         const bf16* gp = A.proj + (grow0 + rr_) * INC + C_MG + hm * 128 + r32; bf16* yp = A.y + (grow0 + rr_) * DM + Y_M + hm * 128 + r32;
; #pragma unroll
;         for (int d0 = 0; d0 < 4; ++d0) { const float g = bf2f(gp[d0 * 32]); const float val = o[d0][r] * rl * silu(g);
;             yp[d0 * 32] = (bf16)(cvtpk(val, val) & 0xffffu); } }
;     __syncthreads();
	v_mov_b32_e32 v4, v88
	v_lshlrev_b64 v[0:1], 12, v[0:1]
	v_lshl_add_u64 v[0:1], s[82:83], 0, v[0:1]
	v_mul_f32_e32 v5, v57, v8
	v_lshl_add_u64 v[0:1], v[0:1], 0, s[84:85]
	v_lshl_add_u64 v[0:1], v[0:1], 0, v[176:177]
	s_nop 0
	v_lshlrev_b32_e32 v4, 16, v4
	v_mul_f32_e32 v16, 0xbfb8aa3b, v4
	v_exp_f32_e32 v16, v16
	s_nop 0
	v_add_f32_e32 v16, 1.0, v16
	v_div_scale_f32 v17, s[0:1], v16, v16, v4
	v_rcp_f32_e32 v18, v17
	s_nop 0
	v_fma_f32 v19, -v17, v18, 1.0
	v_fmac_f32_e32 v18, v19, v18
	v_div_scale_f32 v19, vcc, v4, v16, v4
	v_mul_f32_e32 v20, v19, v18
	v_fma_f32 v21, -v17, v20, v19
	v_fmac_f32_e32 v20, v21, v18
	v_fma_f32 v17, -v17, v20, v19
	v_div_fmas_f32 v17, v17, v18, v20
	v_div_fixup_f32 v4, v17, v16, v4
	v_mul_f32_e32 v4, v5, v4
	v_cvt_pk_bf16_f32 v4, v4, s0
	global_store_short v[0:1], v4, off offset:3072
	s_waitcnt vmcnt(28)
	v_mov_b32_e32 v4, v89
	v_mul_f32_e32 v5, v41, v8
	s_nop 0
	v_lshlrev_b32_e32 v4, 16, v4
	v_mul_f32_e32 v16, 0xbfb8aa3b, v4
	v_exp_f32_e32 v16, v16
	s_nop 0
	v_add_f32_e32 v16, 1.0, v16
	v_div_scale_f32 v17, s[0:1], v16, v16, v4
	v_rcp_f32_e32 v18, v17
	s_nop 0
	v_fma_f32 v19, -v17, v18, 1.0
	v_fmac_f32_e32 v18, v19, v18
	v_div_scale_f32 v19, vcc, v4, v16, v4
	v_mul_f32_e32 v20, v19, v18
	v_fma_f32 v21, -v17, v20, v19
	v_fmac_f32_e32 v20, v21, v18
	v_fma_f32 v17, -v17, v20, v19
	v_div_fmas_f32 v17, v17, v18, v20
	v_div_fixup_f32 v4, v17, v16, v4
	v_mul_f32_e32 v4, v5, v4
	v_cvt_pk_bf16_f32 v4, v4, s0
	global_store_short v[0:1], v4, off offset:3136
	s_waitcnt vmcnt(28)
	v_mov_b32_e32 v4, v90
	v_mul_f32_e32 v5, v25, v8
	s_nop 0
	v_lshlrev_b32_e32 v4, 16, v4
	v_mul_f32_e32 v16, 0xbfb8aa3b, v4
	v_exp_f32_e32 v16, v16
	s_nop 0
	v_add_f32_e32 v16, 1.0, v16
	v_div_scale_f32 v17, s[0:1], v16, v16, v4
	v_rcp_f32_e32 v18, v17
	s_nop 0
	v_fma_f32 v19, -v17, v18, 1.0
	v_fmac_f32_e32 v18, v19, v18
	v_div_scale_f32 v19, vcc, v4, v16, v4
	v_mul_f32_e32 v20, v19, v18
	v_fma_f32 v21, -v17, v20, v19
	v_fmac_f32_e32 v20, v21, v18
	v_fma_f32 v17, -v17, v20, v19
	v_div_fmas_f32 v17, v17, v18, v20
	v_div_fixup_f32 v4, v17, v16, v4
	v_mul_f32_e32 v4, v5, v4
	v_cvt_pk_bf16_f32 v4, v4, s0
	global_store_short v[0:1], v4, off offset:3200
	s_waitcnt vmcnt(28)
	v_mov_b32_e32 v4, v91
	v_mul_f32_e32 v5, v9, v8
	s_nop 0
	v_lshlrev_b32_e32 v4, 16, v4
	v_mul_f32_e32 v6, 0xbfb8aa3b, v4
	v_exp_f32_e32 v6, v6
	s_nop 0
	v_add_f32_e32 v6, 1.0, v6
	v_div_scale_f32 v7, s[0:1], v6, v6, v4
	v_rcp_f32_e32 v8, v7
	s_nop 0
	v_fma_f32 v9, -v7, v8, 1.0
	v_fmac_f32_e32 v8, v9, v8
	v_div_scale_f32 v9, vcc, v4, v6, v4
	v_mul_f32_e32 v16, v9, v8
	v_fma_f32 v17, -v7, v16, v9
	v_fmac_f32_e32 v16, v17, v8
	v_fma_f32 v7, -v7, v16, v9
	v_div_fmas_f32 v7, v7, v8, v16
	v_div_fixup_f32 v4, v7, v6, v4
	v_mul_f32_e32 v4, v5, v4
	v_cvt_pk_bf16_f32 v4, v4, s0
	global_store_short v[0:1], v4, off offset:3264
	v_div_scale_f32 v0, s[0:1], v2, v2, 1.0
	v_rcp_f32_e32 v1, v0
	s_nop 0
	v_fma_f32 v4, -v0, v1, 1.0
	v_fmac_f32_e32 v1, v4, v1
	v_div_scale_f32 v4, vcc, 1.0, v2, 1.0
	v_mul_f32_e32 v5, v4, v1
	v_fma_f32 v6, -v0, v5, v4
	v_fmac_f32_e32 v5, v6, v1
	v_fma_f32 v0, -v0, v5, v4
	v_div_fmas_f32 v0, v0, v1, v5
	v_div_fixup_f32 v2, v0, v2, 1.0
	v_or_b32_e32 v0, 18, v68
	v_mad_u64_u32 v[4:5], s[0:1], v0, s33, v[70:71]
	v_add_u32_e32 v5, s6, v5
	v_lshl_add_u64 v[4:5], v[4:5], 0, s[84:85]
	v_lshl_add_u64 v[4:5], v[4:5], 0, v[176:177]
	v_lshl_add_u64 v[6:7], v[4:5], 0, s[2:3]
	v_add_co_u32_e32 v4, vcc, s63, v4
	v_mov_b32_e32 v1, v69
	s_nop 0
	v_addc_co_u32_e32 v5, vcc, 0, v5, vcc
	s_waitcnt vmcnt(28)
	v_mov_b32_e32 v4, v92
	v_lshlrev_b64 v[0:1], 12, v[0:1]
	v_lshl_add_u64 v[0:1], s[82:83], 0, v[0:1]
	v_mul_f32_e32 v5, v58, v2
	v_lshl_add_u64 v[0:1], v[0:1], 0, s[84:85]
	v_lshl_add_u64 v[0:1], v[0:1], 0, v[176:177]
	s_nop 0
	v_lshlrev_b32_e32 v4, 16, v4
	v_mul_f32_e32 v8, 0xbfb8aa3b, v4
	v_exp_f32_e32 v8, v8
	s_nop 0
	v_add_f32_e32 v8, 1.0, v8
	v_div_scale_f32 v9, s[0:1], v8, v8, v4
	v_rcp_f32_e32 v16, v9
	s_nop 0
	v_fma_f32 v17, -v9, v16, 1.0
	v_fmac_f32_e32 v16, v17, v16
	v_div_scale_f32 v17, vcc, v4, v8, v4
	v_mul_f32_e32 v18, v17, v16
	v_fma_f32 v19, -v9, v18, v17
	v_fmac_f32_e32 v18, v19, v16
	v_fma_f32 v9, -v9, v18, v17
	v_div_fmas_f32 v9, v9, v16, v18
	v_div_fixup_f32 v4, v9, v8, v4
	v_mul_f32_e32 v4, v5, v4
	v_cvt_pk_bf16_f32 v4, v4, s0
	global_store_short v[0:1], v4, off offset:3072
	s_waitcnt vmcnt(28)
	v_mov_b32_e32 v4, v93
	v_mul_f32_e32 v5, v42, v2
	s_nop 0
	v_lshlrev_b32_e32 v4, 16, v4
	v_mul_f32_e32 v8, 0xbfb8aa3b, v4
	v_exp_f32_e32 v8, v8
	s_nop 0
	v_add_f32_e32 v8, 1.0, v8
	v_div_scale_f32 v9, s[0:1], v8, v8, v4
	v_rcp_f32_e32 v16, v9
	s_nop 0
	v_fma_f32 v17, -v9, v16, 1.0
	v_fmac_f32_e32 v16, v17, v16
	v_div_scale_f32 v17, vcc, v4, v8, v4
	v_mul_f32_e32 v18, v17, v16
	v_fma_f32 v19, -v9, v18, v17
	v_fmac_f32_e32 v18, v19, v16
	v_fma_f32 v9, -v9, v18, v17
	v_div_fmas_f32 v9, v9, v16, v18
	v_div_fixup_f32 v4, v9, v8, v4
	v_mul_f32_e32 v4, v5, v4
	v_cvt_pk_bf16_f32 v4, v4, s0
	global_store_short v[0:1], v4, off offset:3136
	s_waitcnt vmcnt(28)
	v_mov_b32_e32 v4, v94
	v_mul_f32_e32 v5, v26, v2
	v_mul_f32_e32 v2, v10, v2
	s_nop 0
	v_lshlrev_b32_e32 v4, 16, v4
	v_mul_f32_e32 v8, 0xbfb8aa3b, v4
	v_exp_f32_e32 v8, v8
	s_nop 0
	v_add_f32_e32 v8, 1.0, v8
	v_div_scale_f32 v9, s[0:1], v8, v8, v4
	v_rcp_f32_e32 v16, v9
	s_nop 0
	v_fma_f32 v17, -v9, v16, 1.0
	v_fmac_f32_e32 v16, v17, v16
	v_div_scale_f32 v17, vcc, v4, v8, v4
	v_mul_f32_e32 v18, v17, v16
	v_fma_f32 v19, -v9, v18, v17
	v_fmac_f32_e32 v18, v19, v16
	v_fma_f32 v9, -v9, v18, v17
	v_div_fmas_f32 v9, v9, v16, v18
	v_div_fixup_f32 v4, v9, v8, v4
	v_mul_f32_e32 v4, v5, v4
	v_cvt_pk_bf16_f32 v4, v4, s0
	global_store_short v[0:1], v4, off offset:3200
	s_waitcnt vmcnt(28)
; __device__ __forceinline__ int crow(int r, int hi) { return (r & 3) + 8 * (r >> 2) + 4 * hi; }
; __device__ __forceinline__ unsigned cvtpk(float lo, float hi) { f32x2_t v = {lo, hi}; bf16x2_t b = __builtin_convertvector(v, bf16x2_t); return __builtin_bit_cast(unsigned, b); }
; __device__ __forceinline__ float bf2f(unsigned short h) { return __uint_as_float(((unsigned)h) << 16); }
; __device__ __forceinline__ float silu(float x) { return x / (1.0f + __expf(-x)); }
; __device__ __forceinline__ void mem_unit(const MemArgs& A, int unit, char* lds, int wv) {
;     ...
;     if (hi == 0) wsl[r32] = l_reg;
;     asm volatile("s_waitcnt lgkmcnt(0)" ::: "memory");
; #pragma unroll
;     for (int r = 0; r < 16; ++r) { const int rr_ = crow(r, hi); const float rl = 1.0f / wsl[rr_];
;         const bf16* gp = A.proj + (grow0 + rr_) * INC + C_MG + hm * 128 + r32; bf16* yp = A.y + (grow0 + rr_) * DM + Y_M + hm * 128 + r32;
; #pragma unroll
;         for (int d0 = 0; d0 < 4; ++d0) { const float g = bf2f(gp[d0 * 32]); const float val = o[d0][r] * rl * silu(g);
;             yp[d0 * 32] = (bf16)(cvtpk(val, val) & 0xffffu); } }
;     __syncthreads();
	v_mov_b32_e32 v4, v95
	s_nop 0
	v_lshlrev_b32_e32 v4, 16, v4
	v_mul_f32_e32 v5, 0xbfb8aa3b, v4
	v_exp_f32_e32 v5, v5
	s_nop 0
	v_add_f32_e32 v5, 1.0, v5
	v_div_scale_f32 v6, s[0:1], v5, v5, v4
	v_rcp_f32_e32 v7, v6
	s_nop 0
	v_fma_f32 v8, -v6, v7, 1.0
	v_fmac_f32_e32 v7, v8, v7
	v_div_scale_f32 v8, vcc, v4, v5, v4
	v_mul_f32_e32 v9, v8, v7
	v_fma_f32 v10, -v6, v9, v8
	v_fmac_f32_e32 v9, v10, v7
	v_fma_f32 v6, -v6, v9, v8
	v_div_fmas_f32 v6, v6, v7, v9
	v_div_fixup_f32 v4, v6, v5, v4
	v_mul_f32_e32 v2, v2, v4
	v_cvt_pk_bf16_f32 v2, v2, s0
	global_store_short v[0:1], v2, off offset:3264
	v_div_scale_f32 v0, s[0:1], v3, v3, 1.0
	v_rcp_f32_e32 v1, v0
	s_nop 0
	v_fma_f32 v2, -v0, v1, 1.0
	v_fmac_f32_e32 v1, v2, v1
	v_div_scale_f32 v2, vcc, 1.0, v3, 1.0
	v_mul_f32_e32 v4, v2, v1
	v_fma_f32 v5, -v0, v4, v2
	v_fmac_f32_e32 v4, v5, v1
	v_fma_f32 v0, -v0, v4, v2
	v_div_fmas_f32 v0, v0, v1, v4
	v_div_fixup_f32 v6, v0, v3, 1.0
	v_or_b32_e32 v0, 19, v68
	v_mad_u64_u32 v[2:3], s[0:1], v0, s33, v[70:71]
	v_add_u32_e32 v3, s6, v3
	v_lshl_add_u64 v[2:3], v[2:3], 0, s[84:85]
	v_lshl_add_u64 v[2:3], v[2:3], 0, v[176:177]
	v_lshl_add_u64 v[4:5], v[2:3], 0, s[2:3]
	v_add_co_u32_e32 v2, vcc, s63, v2
	v_mov_b32_e32 v1, v69
	s_nop 0
	v_addc_co_u32_e32 v3, vcc, 0, v3, vcc
	s_waitcnt vmcnt(28)
	v_mov_b32_e32 v2, v96
	v_lshlrev_b64 v[0:1], 12, v[0:1]
	v_lshl_add_u64 v[0:1], s[82:83], 0, v[0:1]
	v_mul_f32_e32 v3, v59, v6
	v_lshl_add_u64 v[0:1], v[0:1], 0, s[84:85]
	v_lshl_add_u64 v[0:1], v[0:1], 0, v[176:177]
	s_nop 0
	v_lshlrev_b32_e32 v2, 16, v2
	v_mul_f32_e32 v7, 0xbfb8aa3b, v2
	v_exp_f32_e32 v7, v7
	s_nop 0
	v_add_f32_e32 v7, 1.0, v7
	v_div_scale_f32 v8, s[0:1], v7, v7, v2
	v_rcp_f32_e32 v9, v8
	s_nop 0
	v_fma_f32 v10, -v8, v9, 1.0
	v_fmac_f32_e32 v9, v10, v9
	v_div_scale_f32 v10, vcc, v2, v7, v2
	v_mul_f32_e32 v16, v10, v9
	v_fma_f32 v17, -v8, v16, v10
	v_fmac_f32_e32 v16, v17, v9
	v_fma_f32 v8, -v8, v16, v10
	v_div_fmas_f32 v8, v8, v9, v16
	v_div_fixup_f32 v2, v8, v7, v2
	v_mul_f32_e32 v2, v3, v2
	v_cvt_pk_bf16_f32 v2, v2, s0
	global_store_short v[0:1], v2, off offset:3072
	s_waitcnt vmcnt(28)
	v_mov_b32_e32 v2, v97
	v_mul_f32_e32 v3, v43, v6
	s_nop 0
	v_lshlrev_b32_e32 v2, 16, v2
	v_mul_f32_e32 v7, 0xbfb8aa3b, v2
	v_exp_f32_e32 v7, v7
	s_nop 0
	v_add_f32_e32 v7, 1.0, v7
	v_div_scale_f32 v8, s[0:1], v7, v7, v2
	v_rcp_f32_e32 v9, v8
	s_nop 0
	v_fma_f32 v10, -v8, v9, 1.0
	v_fmac_f32_e32 v9, v10, v9
	v_div_scale_f32 v10, vcc, v2, v7, v2
	v_mul_f32_e32 v16, v10, v9
	v_fma_f32 v17, -v8, v16, v10
	v_fmac_f32_e32 v16, v17, v9
	v_fma_f32 v8, -v8, v16, v10
	v_div_fmas_f32 v8, v8, v9, v16
	v_div_fixup_f32 v2, v8, v7, v2
	v_mul_f32_e32 v2, v3, v2
	v_cvt_pk_bf16_f32 v2, v2, s0
	global_store_short v[0:1], v2, off offset:3136
	s_waitcnt vmcnt(28)
	v_mov_b32_e32 v2, v98
	v_mul_f32_e32 v3, v27, v6
	s_nop 0
	v_lshlrev_b32_e32 v2, 16, v2
	v_mul_f32_e32 v7, 0xbfb8aa3b, v2
	v_exp_f32_e32 v7, v7
	s_nop 0
	v_add_f32_e32 v7, 1.0, v7
	v_div_scale_f32 v8, s[0:1], v7, v7, v2
	v_rcp_f32_e32 v9, v8
	s_nop 0
	v_fma_f32 v10, -v8, v9, 1.0
	v_fmac_f32_e32 v9, v10, v9
	v_div_scale_f32 v10, vcc, v2, v7, v2
	v_mul_f32_e32 v16, v10, v9
	v_fma_f32 v17, -v8, v16, v10
	v_fmac_f32_e32 v16, v17, v9
	v_fma_f32 v8, -v8, v16, v10
	v_div_fmas_f32 v8, v8, v9, v16
	v_div_fixup_f32 v2, v8, v7, v2
	v_mul_f32_e32 v2, v3, v2
	v_cvt_pk_bf16_f32 v2, v2, s0
	global_store_short v[0:1], v2, off offset:3200
	s_waitcnt vmcnt(28)
	v_mov_b32_e32 v2, v99
	v_mul_f32_e32 v3, v11, v6
	s_nop 0
	v_lshlrev_b32_e32 v2, 16, v2
	v_mul_f32_e32 v4, 0xbfb8aa3b, v2
	v_exp_f32_e32 v4, v4
	s_nop 0
	v_add_f32_e32 v4, 1.0, v4
	v_div_scale_f32 v5, s[0:1], v4, v4, v2
	v_rcp_f32_e32 v6, v5
	s_nop 0
	v_fma_f32 v7, -v5, v6, 1.0
	v_fmac_f32_e32 v6, v7, v6
	v_div_scale_f32 v7, vcc, v2, v4, v2
	v_mul_f32_e32 v8, v7, v6
	v_fma_f32 v9, -v5, v8, v7
	v_fmac_f32_e32 v8, v9, v6
	v_fma_f32 v5, -v5, v8, v7
	v_div_fmas_f32 v5, v5, v6, v8
	v_div_fixup_f32 v2, v5, v4, v2
	v_mul_f32_e32 v2, v3, v2
	v_cvt_pk_bf16_f32 v2, v2, s0
	global_store_short v[0:1], v2, off offset:3264
	ds_read_b128 v[0:3], v72 offset:96
	s_waitcnt lgkmcnt(0)
	v_div_scale_f32 v4, s[0:1], v0, v0, 1.0
	v_rcp_f32_e32 v5, v4
	s_nop 0
	v_fma_f32 v6, -v4, v5, 1.0
	v_fmac_f32_e32 v5, v6, v5
	v_div_scale_f32 v6, vcc, 1.0, v0, 1.0
	v_mul_f32_e32 v7, v6, v5
	v_fma_f32 v8, -v4, v7, v6
	v_fmac_f32_e32 v7, v8, v5
	v_fma_f32 v4, -v4, v7, v6
	v_div_fmas_f32 v4, v4, v5, v7
	v_div_fixup_f32 v0, v4, v0, 1.0
	v_or_b32_e32 v4, 24, v68
	v_mad_u64_u32 v[6:7], s[0:1], v4, s33, v[70:71]
	v_add_u32_e32 v7, s6, v7
	v_lshl_add_u64 v[6:7], v[6:7], 0, s[84:85]
	v_lshl_add_u64 v[8:9], v[6:7], 0, v[176:177]
	v_lshl_add_u64 v[6:7], v[8:9], 0, s[2:3]
	v_add_co_u32_e32 v8, vcc, s63, v8
	v_mov_b32_e32 v5, v69
	s_nop 0
	v_addc_co_u32_e32 v9, vcc, 0, v9, vcc
	s_waitcnt vmcnt(28)
	v_mov_b32_e32 v8, v100
	v_lshlrev_b64 v[4:5], 12, v[4:5]
	v_lshl_add_u64 v[4:5], s[82:83], 0, v[4:5]
	v_mul_f32_e32 v9, v60, v0
	v_lshl_add_u64 v[4:5], v[4:5], 0, s[84:85]
	v_lshl_add_u64 v[4:5], v[4:5], 0, v[176:177]
	s_nop 0
	v_lshlrev_b32_e32 v8, 16, v8
	v_mul_f32_e32 v10, 0xbfb8aa3b, v8
	v_exp_f32_e32 v10, v10
	s_nop 0
	v_add_f32_e32 v10, 1.0, v10
	v_div_scale_f32 v11, s[0:1], v10, v10, v8
	v_rcp_f32_e32 v16, v11
	s_nop 0
	v_fma_f32 v17, -v11, v16, 1.0
	v_fmac_f32_e32 v16, v17, v16
	v_div_scale_f32 v17, vcc, v8, v10, v8
	v_mul_f32_e32 v18, v17, v16
	v_fma_f32 v19, -v11, v18, v17
	v_fmac_f32_e32 v18, v19, v16
	v_fma_f32 v11, -v11, v18, v17
	v_div_fmas_f32 v11, v11, v16, v18
	v_div_fixup_f32 v8, v11, v10, v8
	v_mul_f32_e32 v8, v9, v8
	v_cvt_pk_bf16_f32 v8, v8, s0
	global_store_short v[4:5], v8, off offset:3072
	s_waitcnt vmcnt(28)
; __device__ __forceinline__ int crow(int r, int hi) { return (r & 3) + 8 * (r >> 2) + 4 * hi; }
; __device__ __forceinline__ unsigned cvtpk(float lo, float hi) { f32x2_t v = {lo, hi}; bf16x2_t b = __builtin_convertvector(v, bf16x2_t); return __builtin_bit_cast(unsigned, b); }
; __device__ __forceinline__ float bf2f(unsigned short h) { return __uint_as_float(((unsigned)h) << 16); }
; __device__ __forceinline__ float silu(float x) { return x / (1.0f + __expf(-x)); }
; __device__ __forceinline__ void mem_unit(const MemArgs& A, int unit, char* lds, int wv) {
;     ...
;     if (hi == 0) wsl[r32] = l_reg;
;     asm volatile("s_waitcnt lgkmcnt(0)" ::: "memory");
; #pragma unroll
;     for (int r = 0; r < 16; ++r) { const int rr_ = crow(r, hi); const float rl = 1.0f / wsl[rr_];
;         const bf16* gp = A.proj + (grow0 + rr_) * INC + C_MG + hm * 128 + r32; bf16* yp = A.y + (grow0 + rr_) * DM + Y_M + hm * 128 + r32;
; #pragma unroll
;         for (int d0 = 0; d0 < 4; ++d0) { const float g = bf2f(gp[d0 * 32]); const float val = o[d0][r] * rl * silu(g);
;             yp[d0 * 32] = (bf16)(cvtpk(val, val) & 0xffffu); } }
;     __syncthreads();
	v_mov_b32_e32 v8, v101
	v_mul_f32_e32 v9, v44, v0
	s_nop 0
	v_lshlrev_b32_e32 v8, 16, v8
	v_mul_f32_e32 v10, 0xbfb8aa3b, v8
	v_exp_f32_e32 v10, v10
	s_nop 0
	v_add_f32_e32 v10, 1.0, v10
	v_div_scale_f32 v11, s[0:1], v10, v10, v8
	v_rcp_f32_e32 v16, v11
	s_nop 0
	v_fma_f32 v17, -v11, v16, 1.0
	v_fmac_f32_e32 v16, v17, v16
	v_div_scale_f32 v17, vcc, v8, v10, v8
	v_mul_f32_e32 v18, v17, v16
	v_fma_f32 v19, -v11, v18, v17
	v_fmac_f32_e32 v18, v19, v16
	v_fma_f32 v11, -v11, v18, v17
	v_div_fmas_f32 v11, v11, v16, v18
	v_div_fixup_f32 v8, v11, v10, v8
	v_mul_f32_e32 v8, v9, v8
	v_cvt_pk_bf16_f32 v8, v8, s0
	global_store_short v[4:5], v8, off offset:3136
	s_waitcnt vmcnt(28)
	v_mov_b32_e32 v8, v102
	v_mul_f32_e32 v9, v28, v0
	s_waitcnt vmcnt(28)
	v_mov_b32_e32 v6, v103
	v_mul_f32_e32 v0, v12, v0
	s_nop 0
	v_lshlrev_b32_e32 v8, 16, v8
	v_mul_f32_e32 v10, 0xbfb8aa3b, v8
	v_exp_f32_e32 v10, v10
	s_nop 0
	v_lshlrev_b32_e32 v6, 16, v6
	v_mul_f32_e32 v7, 0xbfb8aa3b, v6
	v_exp_f32_e32 v7, v7
	v_add_f32_e32 v10, 1.0, v10
	v_div_scale_f32 v11, s[0:1], v10, v10, v8
	v_rcp_f32_e32 v16, v11
	v_add_f32_e32 v7, 1.0, v7
	v_fma_f32 v17, -v11, v16, 1.0
	v_fmac_f32_e32 v16, v17, v16
	v_div_scale_f32 v17, vcc, v8, v10, v8
	v_mul_f32_e32 v18, v17, v16
	v_fma_f32 v19, -v11, v18, v17
	v_fmac_f32_e32 v18, v19, v16
	v_fma_f32 v11, -v11, v18, v17
	v_div_fmas_f32 v11, v11, v16, v18
	v_div_fixup_f32 v8, v11, v10, v8
	v_mul_f32_e32 v8, v9, v8
	v_cvt_pk_bf16_f32 v8, v8, s0
	global_store_short v[4:5], v8, off offset:3200
	v_div_scale_f32 v8, s[0:1], v7, v7, v6
	v_rcp_f32_e32 v9, v8
	s_nop 0
	v_fma_f32 v10, -v8, v9, 1.0
	v_fmac_f32_e32 v9, v10, v9
	v_div_scale_f32 v10, vcc, v6, v7, v6
	v_mul_f32_e32 v11, v10, v9
	v_fma_f32 v12, -v8, v11, v10
	v_fmac_f32_e32 v11, v12, v9
	v_fma_f32 v8, -v8, v11, v10
	v_div_fmas_f32 v8, v8, v9, v11
	v_div_fixup_f32 v6, v8, v7, v6
	v_mul_f32_e32 v0, v0, v6
	v_cvt_pk_bf16_f32 v0, v0, s0
	global_store_short v[4:5], v0, off offset:3264
	v_div_scale_f32 v0, s[0:1], v1, v1, 1.0
	v_rcp_f32_e32 v4, v0
	s_nop 0
	v_fma_f32 v5, -v0, v4, 1.0
	v_fmac_f32_e32 v4, v5, v4
	v_div_scale_f32 v5, vcc, 1.0, v1, 1.0
	v_mul_f32_e32 v6, v5, v4
	v_fma_f32 v7, -v0, v6, v5
	v_fmac_f32_e32 v6, v7, v4
	v_fma_f32 v0, -v0, v6, v5
	v_div_fmas_f32 v0, v0, v4, v6
	v_div_fixup_f32 v6, v0, v1, 1.0
	v_or_b32_e32 v0, 25, v68
	v_mad_u64_u32 v[4:5], s[0:1], v0, s33, v[70:71]
	v_add_u32_e32 v5, s6, v5
	v_lshl_add_u64 v[4:5], v[4:5], 0, s[84:85]
	v_lshl_add_u64 v[8:9], v[4:5], 0, v[176:177]
	v_lshl_add_u64 v[4:5], v[8:9], 0, s[2:3]
	v_add_co_u32_e32 v8, vcc, s63, v8
	v_mov_b32_e32 v1, v69
	s_nop 0
	v_addc_co_u32_e32 v9, vcc, 0, v9, vcc
	s_waitcnt vmcnt(28)
	v_mov_b32_e32 v7, v104
	v_lshlrev_b64 v[0:1], 12, v[0:1]
	v_lshl_add_u64 v[0:1], s[82:83], 0, v[0:1]
	v_mul_f32_e32 v8, v61, v6
	v_lshl_add_u64 v[0:1], v[0:1], 0, s[84:85]
	v_lshl_add_u64 v[0:1], v[0:1], 0, v[176:177]
	s_nop 0
	v_lshlrev_b32_e32 v7, 16, v7
	v_mul_f32_e32 v9, 0xbfb8aa3b, v7
	v_exp_f32_e32 v9, v9
	s_nop 0
	v_add_f32_e32 v9, 1.0, v9
	v_div_scale_f32 v10, s[0:1], v9, v9, v7
	v_rcp_f32_e32 v11, v10
	s_nop 0
	v_fma_f32 v12, -v10, v11, 1.0
	v_fmac_f32_e32 v11, v12, v11
	v_div_scale_f32 v12, vcc, v7, v9, v7
	v_mul_f32_e32 v16, v12, v11
	v_fma_f32 v17, -v10, v16, v12
	v_fmac_f32_e32 v16, v17, v11
	v_fma_f32 v10, -v10, v16, v12
	v_div_fmas_f32 v10, v10, v11, v16
	v_div_fixup_f32 v7, v10, v9, v7
	v_mul_f32_e32 v7, v8, v7
	v_cvt_pk_bf16_f32 v7, v7, s0
	global_store_short v[0:1], v7, off offset:3072
	s_waitcnt vmcnt(28)
	v_mov_b32_e32 v7, v105
	v_mul_f32_e32 v8, v45, v6
	s_nop 0
	v_lshlrev_b32_e32 v7, 16, v7
	v_mul_f32_e32 v9, 0xbfb8aa3b, v7
	v_exp_f32_e32 v9, v9
	s_nop 0
	v_add_f32_e32 v9, 1.0, v9
	v_div_scale_f32 v10, s[0:1], v9, v9, v7
	v_rcp_f32_e32 v11, v10
	s_nop 0
	v_fma_f32 v12, -v10, v11, 1.0
	v_fmac_f32_e32 v11, v12, v11
	v_div_scale_f32 v12, vcc, v7, v9, v7
	v_mul_f32_e32 v16, v12, v11
	v_fma_f32 v17, -v10, v16, v12
	v_fmac_f32_e32 v16, v17, v11
	v_fma_f32 v10, -v10, v16, v12
	v_div_fmas_f32 v10, v10, v11, v16
	v_div_fixup_f32 v7, v10, v9, v7
	v_mul_f32_e32 v7, v8, v7
	v_cvt_pk_bf16_f32 v7, v7, s0
	global_store_short v[0:1], v7, off offset:3136
	s_waitcnt vmcnt(28)
	v_mov_b32_e32 v7, v106
	v_mul_f32_e32 v8, v29, v6
	s_waitcnt vmcnt(28)
	v_mov_b32_e32 v4, v107
	v_mul_f32_e32 v5, v13, v6
	s_nop 0
	v_lshlrev_b32_e32 v7, 16, v7
	v_mul_f32_e32 v9, 0xbfb8aa3b, v7
	v_exp_f32_e32 v9, v9
	s_nop 0
	v_lshlrev_b32_e32 v4, 16, v4
	v_mul_f32_e32 v6, 0xbfb8aa3b, v4
	v_exp_f32_e32 v6, v6
	v_add_f32_e32 v9, 1.0, v9
	v_div_scale_f32 v10, s[0:1], v9, v9, v7
	v_rcp_f32_e32 v11, v10
	v_add_f32_e32 v6, 1.0, v6
	v_fma_f32 v12, -v10, v11, 1.0
	v_fmac_f32_e32 v11, v12, v11
	v_div_scale_f32 v12, vcc, v7, v9, v7
	v_mul_f32_e32 v16, v12, v11
	v_fma_f32 v17, -v10, v16, v12
	v_fmac_f32_e32 v16, v17, v11
	v_fma_f32 v10, -v10, v16, v12
	v_div_fmas_f32 v10, v10, v11, v16
	v_div_fixup_f32 v7, v10, v9, v7
	v_mul_f32_e32 v7, v8, v7
	v_cvt_pk_bf16_f32 v7, v7, s0
	global_store_short v[0:1], v7, off offset:3200
	v_div_scale_f32 v7, s[0:1], v6, v6, v4
	v_rcp_f32_e32 v8, v7
	s_nop 0
	v_fma_f32 v9, -v7, v8, 1.0
	v_fmac_f32_e32 v8, v9, v8
	v_div_scale_f32 v9, vcc, v4, v6, v4
	v_mul_f32_e32 v10, v9, v8
	v_fma_f32 v11, -v7, v10, v9
	v_fmac_f32_e32 v10, v11, v8
	v_fma_f32 v7, -v7, v10, v9
	v_div_fmas_f32 v7, v7, v8, v10
	v_div_fixup_f32 v4, v7, v6, v4
	v_mul_f32_e32 v4, v5, v4
	v_cvt_pk_bf16_f32 v4, v4, s0
	global_store_short v[0:1], v4, off offset:3264
	v_div_scale_f32 v0, s[0:1], v2, v2, 1.0
	v_rcp_f32_e32 v1, v0
	s_nop 0
	v_fma_f32 v4, -v0, v1, 1.0
	v_fmac_f32_e32 v1, v4, v1
	v_div_scale_f32 v4, vcc, 1.0, v2, 1.0
	v_mul_f32_e32 v5, v4, v1
	v_fma_f32 v6, -v0, v5, v4
	v_fmac_f32_e32 v5, v6, v1
	v_fma_f32 v0, -v0, v5, v4
	v_div_fmas_f32 v0, v0, v1, v5
	v_div_fixup_f32 v2, v0, v2, 1.0
	v_or_b32_e32 v0, 26, v68
	v_mad_u64_u32 v[4:5], s[0:1], v0, s33, v[70:71]
	v_add_u32_e32 v5, s6, v5
	v_lshl_add_u64 v[4:5], v[4:5], 0, s[84:85]
	v_lshl_add_u64 v[6:7], v[4:5], 0, v[176:177]
	v_lshl_add_u64 v[4:5], v[6:7], 0, s[2:3]
	v_add_co_u32_e32 v6, vcc, s63, v6
	v_mov_b32_e32 v1, v69
	s_nop 0
	v_addc_co_u32_e32 v7, vcc, 0, v7, vcc
	s_waitcnt vmcnt(28)
; __device__ __forceinline__ int crow(int r, int hi) { return (r & 3) + 8 * (r >> 2) + 4 * hi; }
; __device__ __forceinline__ unsigned cvtpk(float lo, float hi) { f32x2_t v = {lo, hi}; bf16x2_t b = __builtin_convertvector(v, bf16x2_t); return __builtin_bit_cast(unsigned, b); }
; __device__ __forceinline__ float bf2f(unsigned short h) { return __uint_as_float(((unsigned)h) << 16); }
; __device__ __forceinline__ float silu(float x) { return x / (1.0f + __expf(-x)); }
; __device__ __forceinline__ void mem_unit(const MemArgs& A, int unit, char* lds, int wv) {
;     ...
;     if (hi == 0) wsl[r32] = l_reg;
;     asm volatile("s_waitcnt lgkmcnt(0)" ::: "memory");
; #pragma unroll
;     for (int r = 0; r < 16; ++r) { const int rr_ = crow(r, hi); const float rl = 1.0f / wsl[rr_];
;         const bf16* gp = A.proj + (grow0 + rr_) * INC + C_MG + hm * 128 + r32; bf16* yp = A.y + (grow0 + rr_) * DM + Y_M + hm * 128 + r32;
; #pragma unroll
;         for (int d0 = 0; d0 < 4; ++d0) { const float g = bf2f(gp[d0 * 32]); const float val = o[d0][r] * rl * silu(g);
;             yp[d0 * 32] = (bf16)(cvtpk(val, val) & 0xffffu); } }
;     __syncthreads();
	v_mov_b32_e32 v6, v108
	v_lshlrev_b64 v[0:1], 12, v[0:1]
	v_lshl_add_u64 v[0:1], s[82:83], 0, v[0:1]
	v_mul_f32_e32 v7, v62, v2
	v_lshl_add_u64 v[0:1], v[0:1], 0, s[84:85]
	v_lshl_add_u64 v[0:1], v[0:1], 0, v[176:177]
	v_or_b32_e32 v68, 27, v68
	s_nop 0
	v_lshlrev_b32_e32 v6, 16, v6
	v_mul_f32_e32 v8, 0xbfb8aa3b, v6
	v_exp_f32_e32 v8, v8
	s_nop 0
	v_add_f32_e32 v8, 1.0, v8
	v_div_scale_f32 v9, s[0:1], v8, v8, v6
	v_rcp_f32_e32 v10, v9
	s_nop 0
	v_fma_f32 v11, -v9, v10, 1.0
	v_fmac_f32_e32 v10, v11, v10
	v_div_scale_f32 v11, vcc, v6, v8, v6
	v_mul_f32_e32 v12, v11, v10
	v_fma_f32 v13, -v9, v12, v11
	v_fmac_f32_e32 v12, v13, v10
	v_fma_f32 v9, -v9, v12, v11
	v_div_fmas_f32 v9, v9, v10, v12
	v_div_fixup_f32 v6, v9, v8, v6
	v_mul_f32_e32 v6, v7, v6
	v_cvt_pk_bf16_f32 v6, v6, s0
	global_store_short v[0:1], v6, off offset:3072
	s_waitcnt vmcnt(28)
	v_mov_b32_e32 v6, v109
	v_mul_f32_e32 v7, v46, v2
	s_nop 0
	v_lshlrev_b32_e32 v6, 16, v6
	v_mul_f32_e32 v8, 0xbfb8aa3b, v6
	v_exp_f32_e32 v8, v8
	s_nop 0
	v_add_f32_e32 v8, 1.0, v8
	v_div_scale_f32 v9, s[0:1], v8, v8, v6
	v_rcp_f32_e32 v10, v9
	s_nop 0
	v_fma_f32 v11, -v9, v10, 1.0
	v_fmac_f32_e32 v10, v11, v10
	v_div_scale_f32 v11, vcc, v6, v8, v6
	v_mul_f32_e32 v12, v11, v10
	v_fma_f32 v13, -v9, v12, v11
	v_fmac_f32_e32 v12, v13, v10
	v_fma_f32 v9, -v9, v12, v11
	v_div_fmas_f32 v9, v9, v10, v12
	v_div_fixup_f32 v6, v9, v8, v6
	v_mul_f32_e32 v6, v7, v6
	v_cvt_pk_bf16_f32 v6, v6, s0
	global_store_short v[0:1], v6, off offset:3136
	s_waitcnt vmcnt(28)
	v_mov_b32_e32 v6, v110
	v_mul_f32_e32 v7, v30, v2
	s_waitcnt vmcnt(28)
	v_mov_b32_e32 v4, v111
	v_mul_f32_e32 v2, v14, v2
	s_nop 0
	v_lshlrev_b32_e32 v6, 16, v6
	v_mul_f32_e32 v8, 0xbfb8aa3b, v6
	v_exp_f32_e32 v8, v8
	s_nop 0
	v_lshlrev_b32_e32 v4, 16, v4
	v_mul_f32_e32 v5, 0xbfb8aa3b, v4
	v_exp_f32_e32 v5, v5
	v_add_f32_e32 v8, 1.0, v8
	v_div_scale_f32 v9, s[0:1], v8, v8, v6
	v_rcp_f32_e32 v10, v9
	v_add_f32_e32 v5, 1.0, v5
	v_fma_f32 v11, -v9, v10, 1.0
	v_fmac_f32_e32 v10, v11, v10
	v_div_scale_f32 v11, vcc, v6, v8, v6
	v_mul_f32_e32 v12, v11, v10
	v_fma_f32 v13, -v9, v12, v11
	v_fmac_f32_e32 v12, v13, v10
	v_fma_f32 v9, -v9, v12, v11
	v_div_fmas_f32 v9, v9, v10, v12
	v_div_fixup_f32 v6, v9, v8, v6
	v_mul_f32_e32 v6, v7, v6
	v_cvt_pk_bf16_f32 v6, v6, s0
	global_store_short v[0:1], v6, off offset:3200
	v_div_scale_f32 v6, s[0:1], v5, v5, v4
	v_rcp_f32_e32 v7, v6
	s_nop 0
	v_fma_f32 v8, -v6, v7, 1.0
	v_fmac_f32_e32 v7, v8, v7
	v_div_scale_f32 v8, vcc, v4, v5, v4
	v_mul_f32_e32 v9, v8, v7
	v_fma_f32 v10, -v6, v9, v8
	v_fmac_f32_e32 v9, v10, v7
	v_fma_f32 v6, -v6, v9, v8
	v_div_fmas_f32 v6, v6, v7, v9
	v_div_fixup_f32 v4, v6, v5, v4
	v_mul_f32_e32 v2, v2, v4
	v_cvt_pk_bf16_f32 v2, v2, s0
	global_store_short v[0:1], v2, off offset:3264
	v_div_scale_f32 v0, s[0:1], v3, v3, 1.0
	v_rcp_f32_e32 v1, v0
	s_nop 0
	v_fma_f32 v2, -v0, v1, 1.0
	v_fmac_f32_e32 v1, v2, v1
	v_div_scale_f32 v2, vcc, 1.0, v3, 1.0
	v_mul_f32_e32 v4, v2, v1
	v_fma_f32 v5, -v0, v4, v2
	v_fmac_f32_e32 v4, v5, v1
	v_fma_f32 v0, -v0, v4, v2
	v_div_fmas_f32 v0, v0, v1, v4
	v_div_fixup_f32 v4, v0, v3, 1.0
	v_mad_u64_u32 v[0:1], s[0:1], v68, s33, v[70:71]
	v_add_u32_e32 v1, s6, v1
	v_lshl_add_u64 v[0:1], v[0:1], 0, s[84:85]
	v_lshl_add_u64 v[6:7], v[0:1], 0, v[176:177]
	v_lshl_add_u64 v[2:3], v[6:7], 0, s[2:3]
	v_add_co_u32_e32 v6, vcc, s63, v6
	v_lshlrev_b64 v[0:1], 12, v[68:69]
	s_nop 0
	v_addc_co_u32_e32 v7, vcc, 0, v7, vcc
	s_waitcnt vmcnt(28)
	v_mov_b32_e32 v5, v157
	v_lshl_add_u64 v[0:1], s[82:83], 0, v[0:1]
	v_mul_f32_e32 v6, v63, v4
	v_lshl_add_u64 v[0:1], v[0:1], 0, s[84:85]
	v_lshl_add_u64 v[0:1], v[0:1], 0, v[176:177]
	s_mov_b64 s[6:7], 0
	s_nop 0
	v_lshlrev_b32_e32 v5, 16, v5
	v_mul_f32_e32 v7, 0xbfb8aa3b, v5
	v_exp_f32_e32 v7, v7
	s_nop 0
	v_add_f32_e32 v7, 1.0, v7
	v_div_scale_f32 v8, s[0:1], v7, v7, v5
	v_rcp_f32_e32 v9, v8
	s_nop 0
	v_fma_f32 v10, -v8, v9, 1.0
	v_fmac_f32_e32 v9, v10, v9
	v_div_scale_f32 v10, vcc, v5, v7, v5
	v_mul_f32_e32 v11, v10, v9
	v_fma_f32 v12, -v8, v11, v10
	v_fmac_f32_e32 v11, v12, v9
	v_fma_f32 v8, -v8, v11, v10
	v_div_fmas_f32 v8, v8, v9, v11
	v_div_fixup_f32 v5, v8, v7, v5
	v_mul_f32_e32 v5, v6, v5
	v_cvt_pk_bf16_f32 v5, v5, s0
	global_store_short v[0:1], v5, off offset:3072
	s_waitcnt vmcnt(28)
	v_mov_b32_e32 v5, v158
	v_mul_f32_e32 v6, v47, v4
	s_nop 0
	v_lshlrev_b32_e32 v5, 16, v5
	v_mul_f32_e32 v7, 0xbfb8aa3b, v5
	v_exp_f32_e32 v7, v7
	s_nop 0
	v_add_f32_e32 v7, 1.0, v7
	v_div_scale_f32 v8, s[0:1], v7, v7, v5
	v_rcp_f32_e32 v9, v8
	s_nop 0
	v_fma_f32 v10, -v8, v9, 1.0
	v_fmac_f32_e32 v9, v10, v9
	v_div_scale_f32 v10, vcc, v5, v7, v5
	v_mul_f32_e32 v11, v10, v9
	v_fma_f32 v12, -v8, v11, v10
	v_fmac_f32_e32 v11, v12, v9
	v_fma_f32 v8, -v8, v11, v10
	v_div_fmas_f32 v8, v8, v9, v11
	v_div_fixup_f32 v5, v8, v7, v5
	v_mul_f32_e32 v5, v6, v5
	v_cvt_pk_bf16_f32 v5, v5, s0
	global_store_short v[0:1], v5, off offset:3136
	s_waitcnt vmcnt(28)
	v_mov_b32_e32 v5, v159
	v_mul_f32_e32 v6, v31, v4
	s_waitcnt vmcnt(28)
	v_mov_b32_e32 v2, v160
	v_mul_f32_e32 v3, v15, v4
	s_nop 0
	v_lshlrev_b32_e32 v5, 16, v5
	v_mul_f32_e32 v7, 0xbfb8aa3b, v5
	v_exp_f32_e32 v7, v7
	s_nop 0
	v_lshlrev_b32_e32 v2, 16, v2
	v_mul_f32_e32 v4, 0xbfb8aa3b, v2
	v_exp_f32_e32 v4, v4
	v_add_f32_e32 v7, 1.0, v7
	v_div_scale_f32 v8, s[0:1], v7, v7, v5
	v_rcp_f32_e32 v9, v8
	v_add_f32_e32 v4, 1.0, v4
	v_fma_f32 v10, -v8, v9, 1.0
	v_fmac_f32_e32 v9, v10, v9
	v_div_scale_f32 v10, vcc, v5, v7, v5
	v_mul_f32_e32 v11, v10, v9
	v_fma_f32 v12, -v8, v11, v10
	v_fmac_f32_e32 v11, v12, v9
	v_fma_f32 v8, -v8, v11, v10
	v_div_fmas_f32 v8, v8, v9, v11
	v_div_fixup_f32 v5, v8, v7, v5
	v_mul_f32_e32 v5, v6, v5
	v_cvt_pk_bf16_f32 v5, v5, s0
	global_store_short v[0:1], v5, off offset:3200
	v_div_scale_f32 v5, s[0:1], v4, v4, v2
	v_rcp_f32_e32 v6, v5
	s_nop 0
	v_fma_f32 v7, -v5, v6, 1.0
	v_fmac_f32_e32 v6, v7, v6
	v_div_scale_f32 v7, vcc, v2, v4, v2
	v_mul_f32_e32 v8, v7, v6
	v_fma_f32 v9, -v5, v8, v7
	v_fmac_f32_e32 v8, v9, v6
	v_fma_f32 v5, -v5, v8, v7
	v_div_fmas_f32 v5, v5, v6, v8
	v_div_fixup_f32 v2, v5, v4, v2
	v_mul_f32_e32 v2, v3, v2
	v_cvt_pk_bf16_f32 v2, v2, s0
	global_store_short v[0:1], v2, off offset:3264
	s_barrier
